# speedup vs baseline: 1.0286x; 1.0028x over previous
; __device__ __forceinline__ int v_st(int k, int c) { const int kk = (k & ~0xC) | ((k & 4) << 1) | ((k & 8) >> 1); return ((kk >> 3) * 4 + (c >> 5)) * 512 + ((kk & 7) * 32 + (c & 31)) * 2; }
; __device__ __forceinline__ int v_rd_base(int lane) { return ((lane & 3) << 3) | (((lane >> 2) & 3) << 6) | (((lane >> 4) & 1) << 5) | (((lane >> 5) & 1) << 8); }
; template <bool META>
; __device__ __forceinline__ void attn_unit(const bf16_t* Q, bf16_t* Oo, const bf16_t* __restrict__ Kb, const bf16_t* __restrict__ Vb, int b, int kvh, int h, int qb, char* lds, const int tid, const float* qn, const float* RT) {
;     ...
;   const int wid = tid >> 6, lane = tid & 63, r32 = lane & 31, hi = lane >> 5;
;   bf16_t* V_lds = (bf16_t*)lds; bf16_t* K_lds = (bf16_t*)(lds + 3 * SHM_V);
;   float* ws = (float*)(lds + 3 * SHM_V + 3 * SHM_K) + wid * 64; float* li_l = ws; float* al_l = ws + 32;
;   float m_reg = -1e30f, l_reg = 0; f32x16 o[4] = {}; bf16x8 qr[8];
;   const bf16_t* Kh = Kb + kvh * 128; const bf16_t* Vh = Vb + kvh * 128;
;   const long kv0 = (long)b * SEQ, mrow = NREAL + NMETA * b;
;   { const int sq = qb * 256 + wid * 32 + r32;
;     load_q_roped(Q + (size_t)(b * SEQ + sq) * 1024 + h * 128 + hi * 8, qn + hi * 8, RT, sq >> 6, sq & 63, hi, lane, qr); }
;   const int sr = tid >> 4, sc = (tid & 15) * 8, vst0 = v_st(sr, sc), vst1 = v_st(32 + sr, sc);
;   const int vb0 = (int)(uintptr_t)V_lds + v_rd_base(lane);
;   const unsigned lo0 = (unsigned)(sr * LDK + sc) * 2u;
.LBB0_255:
	s_and_b64 vcc, exec, s[0:1]
	s_cbranch_vccz .LBB0_348
	s_cmpk_gt_i32 s50, 0x3ff
	s_cbranch_scc1 .LBB0_274
	v_readlane_b32 s0, v255, 13
	s_lshl_b32 s0, s0, 7
	s_ashr_i32 s1, s0, 31
	s_lshl_b64 s[0:1], s[0:1], 2
	s_add_u32 s0, s68, s0
	s_addc_u32 s1, s69, s1
	v_readlane_b32 s2, v255, 24
	v_readlane_b32 s3, v255, 25
	s_add_u32 s48, s2, 0x3d7f5100
	s_addc_u32 s49, s3, 0
	v_and_b32_e32 v0, 0x3fffffc0, v208
	s_add_i32 s2, 0, 0x18000
	v_lshl_add_u32 v173, v0, 2, s2
	v_ashrrev_i32_e32 v0, 1, v208
	v_and_b32_e32 v2, 63, v208
	v_and_b32_e32 v172, 0xffffffe0, v0
	v_and_b32_e32 v0, 32, v208
	v_lshl_add_u64 v[164:165], s[0:1], 0, v[0:1]
	v_lshlrev_b32_e32 v0, 2, v2
	v_xor_b32_e32 v252, 0x80, v0
	v_ashrrev_i32_e32 v0, 4, v208
	v_and_b32_e32 v5, 0xfffff0, v0
	s_waitcnt vmcnt(0)
	v_lshlrev_b32_e32 v6, 1, v0
	s_waitcnt lgkmcnt(0)
	v_lshlrev_b32_e32 v3, 3, v208
	v_and_or_b32 v5, v6, 8, v5
	v_and_b32_e32 v4, 0x78, v3
	v_lshrrev_b32_e32 v6, 1, v0
	v_lshrrev_b32_e32 v5, 1, v5
	v_bfe_u32 v3, v3, 5, 2
	v_and_b32_e32 v7, 3, v0
	v_or_b32_e32 v5, v5, v3
	v_and_or_b32 v6, v6, 4, v7
	v_lshlrev_b32_e32 v7, 1, v4
	v_lshlrev_b32_e32 v5, 9, v5
	v_lshlrev_b32_e32 v6, 6, v6
	v_and_b32_e32 v8, 48, v7
	v_or3_b32 v176, v5, v6, v8
	v_add_u32_e32 v5, 32, v0
	v_and_b32_e32 v9, 0xfffff0, v5
	v_lshlrev_b32_e32 v10, 1, v5
	v_and_or_b32 v9, v10, 8, v9
	v_lshrrev_b32_e32 v9, 1, v9
	v_or_b32_e32 v3, v9, v3
	v_lshlrev_b32_e32 v3, 9, v3
	v_or3_b32 v177, v3, v6, v8
	v_lshlrev_b32_e32 v6, 4, v208
	v_lshlrev_b32_e32 v3, 3, v2
	v_and_b32_e32 v8, 0xc0, v6
	v_lshlrev_b32_e32 v9, 1, v208
	v_and_or_b32 v8, v3, 24, v8
	v_and_b32_e32 v9, 32, v9
	v_and_b32_e32 v3, 0x100, v3
	s_cmp_lg_u32 0, -1
	v_or3_b32 v3, v8, v9, v3
	s_cselect_b32 s0, 0, 0
	v_lshlrev_b32_e32 v0, 8, v0
	v_add_u32_e32 v178, s0, v3
	v_or_b32_e32 v3, v0, v4
	v_bfe_u32 v11, v208, 5, 1
	v_lshlrev_b32_e32 v166, 1, v3
	v_and_b32_e32 v3, 0xf0, v208
	v_and_b32_e32 v163, 31, v208
	v_bitop3_b32 v179, v7, v0, v3 bitop3:0xde
	v_lshlrev_b32_e32 v0, 8, v5
	v_lshlrev_b32_e32 v181, 4, v11
	v_bitop3_b32 v180, v7, v0, v3 bitop3:0xde
	v_lshlrev_b32_e32 v0, 8, v163
	v_and_b32_e32 v3, 0xf0, v6
	v_or_b32_e32 v4, 32, v181
	v_bitop3_b32 v183, v4, v0, v3 bitop3:0xde
	v_or_b32_e32 v4, 64, v181
	v_bitop3_b32 v184, v4, v0, v3 bitop3:0xde
	v_or_b32_e32 v4, 0x60, v181
	v_bitop3_b32 v185, v4, v0, v3 bitop3:0xde
	v_or_b32_e32 v4, 0x80, v181
	v_bitop3_b32 v186, v4, v0, v3 bitop3:0xde
	v_or_b32_e32 v4, 0xa0, v181
	v_bitop3_b32 v187, v4, v0, v3 bitop3:0xde
	v_or_b32_e32 v4, 0xc0, v181
	v_bitop3_b32 v188, v4, v0, v3 bitop3:0xde
	v_or_b32_e32 v4, 0xe0, v181
	v_lshlrev_b32_e32 v162, 3, v11
	v_mov_b32_e32 v167, v1
	v_bitop3_b32 v182, v181, v0, v3 bitop3:0xde
	v_bitop3_b32 v189, v4, v0, v3 bitop3:0xde
	v_cmp_gt_u32_e64 s[38:39], 32, v2
	v_lshl_add_u32 v190, v163, 2, v173
	v_and_b32_e32 v230, 63, v208
	v_lshrrev_b32_e32 v231, 6, v208
	v_lshlrev_b32_e32 v231, 2, v231
	v_lshrrev_b32_e32 v232, 5, v230
	v_bfe_u32 v233, v230, 2, 1
	v_lshl_add_u32 v234, v232, 1, v231
	v_add_u32_e32 v234, v234, v233
	v_bfe_u32 v235, v230, 3, 2
	v_and_b32_e32 v236, 3, v230
	v_lshl_add_u32 v235, v235, 2, v236
	v_lshlrev_b32_e32 v166, 9, v234
	v_lshl_add_u32 v166, v235, 4, v166
	v_and_b32_e32 v232, 0x13, v234
	v_and_b32_e32 v233, 4, v234
	v_lshlrev_b32_e32 v233, 1, v233
	v_and_b32_e32 v236, 8, v234
	v_lshrrev_b32_e32 v236, 1, v236
	v_or3_b32 v232, v232, v233, v236
	v_lshrrev_b32_e32 v233, 3, v232
	v_lshrrev_b32_e32 v236, 2, v235
	v_lshl_add_u32 v233, v233, 2, v236
	v_lshlrev_b32_e32 v233, 9, v233
	v_and_b32_e32 v236, 7, v232
	v_lshl_add_u32 v233, v236, 6, v233
	v_and_b32_e32 v236, 3, v235
	v_lshl_add_u32 v176, v236, 4, v233
	v_add_u32_e32 v177, 0x2000, v176
	v_bfe_u32 v232, v230, 1, 2
	v_add_u32_e32 v232, v232, v231
	v_lshrrev_b32_e32 v233, 3, v230
	v_and_b32_e32 v236, 1, v230
	v_lshl_add_u32 v233, v233, 1, v236
	v_lshlrev_b32_e32 v184, 9, v232
	v_lshl_add_u32 v184, v233, 4, v184
	v_mov_b32_e32 v185, v1
	v_add_u32_e32 v186, 0x4000, v184
	v_lshrrev_b32_e32 v234, 1, v233
	v_lshlrev_b32_e32 v234, 11, v234
	v_lshl_add_u32 v234, v232, 5, v234
	v_bfe_u32 v235, v232, 3, 1
	v_xor_b32_e32 v235, v235, v236
	v_lshl_or_b32 v179, v235, 4, v234
	v_add_u32_e32 v180, 0x400, v179
	v_and_b32_e32 v232, 31, v208
	v_lshlrev_b32_e32 v233, 5, v232
	v_bfe_u32 v234, v208, 5, 1
	v_bfe_u32 v235, v208, 3, 1
	v_xor_b32_e32 v234, v234, v235
	v_lshl_or_b32 v182, v234, 4, v233
	s_mov_b32 s2, s50
	s_branch .LBB0_259

; __device__ __forceinline__ float bflo(unsigned w) { return __uint_as_float(w << 16); }
; __device__ __forceinline__ float bfhi(unsigned w) { return __uint_as_float(w & 0xffff0000u); }
; __device__ __forceinline__ float lane_read(float v, int src) { return __int_as_float(__builtin_amdgcn_ds_bpermute(src << 2, __float_as_int(v))); }
; __device__ __forceinline__ void load_q_roped(const bf16_t* Qw, const float* __restrict__ wq, const float* __restrict__ RT, int pr, int pc, int hi, int lane, bf16x8 (&qr)[8]) {
;   float y[8][8]; float ss = 0.f;
; #pragma unroll
;   for (int d0 = 0; d0 < 8; ++d0) { const u32x4 w = *(const u32x4*)(Qw + d0 * 16);
; #pragma unroll
;     for (int q = 0; q < 4; ++q) { y[d0][2 * q] = bflo(w[q]); y[d0][2 * q + 1] = bfhi(w[q]); } }
; #pragma unroll
;   for (int d0 = 0; d0 < 8; ++d0)
; #pragma unroll
;     for (int e = 0; e < 8; ++e) ss += y[d0][e] * y[d0][e];
;   ss += lane_read(ss, lane ^ 32);
;   const float rstd = __builtin_amdgcn_rsqf(ss * (1.f / 128.f) + 1e-6f);
; #pragma unroll
;   for (int d0 = 0; d0 < 8; ++d0) { const f32x4 w0 = *(const f32x4*)(wq + d0 * 16), w1 = *(const f32x4*)(wq + d0 * 16 + 4);
; #pragma unroll
;     for (int e = 0; e < 8; ++e) y[d0][e] *= rstd * (e < 4 ? w0[e & 3] : w1[e & 3]); }
; #pragma unroll
;   for (int hf = 0; hf < 2; ++hf)
; #pragma unroll
;     for (int lo = 0; lo < 2; ++lo) { const int d0 = hf * 4 + lo;
;       const float* tp = RT + (size_t)((hf ? pc : pr) * 32 + lo * 16 + hi * 8) * 2;
;       f32x4 t[4];
; #pragma unroll
;       for (int q = 0; q < 4; ++q) t[q] = *(const f32x4*)(tp + 4 * q);
.LBB0_259:
	s_bfe_u32 s1, s2, 0x10008
	s_ashr_i32 s0, s2, 9
	s_lshl_b32 s3, s1, 8
	v_readlane_b32 s6, v255, 9
	v_readlane_b32 s7, v255, 10
	s_add_u32 s40, s6, s3
	s_addc_u32 s41, s7, 0
	v_readlane_b32 s6, v255, 5
	v_readlane_b32 s7, v255, 6
	s_add_u32 s42, s6, s3
	s_addc_u32 s43, s7, 0
	s_lshl_b32 s3, s2, 6
	s_and_b32 s3, s3, 0x3f00
	v_add_u32_e32 v191, s3, v172
	v_or_b32_e32 v21, v191, v163
	s_lshl_b32 s3, s0, 14
	v_add_u32_e32 v2, s3, v21
	s_lshl_b32 s4, s2, 7
	v_ashrrev_i32_e32 v3, 31, v2
	s_lshl_b32 s1, s1, 9
	s_and_b32 s4, s4, 0x180
	v_lshlrev_b64 v[2:3], 11, v[2:3]
	s_or_b32 s30, s1, s4
	v_lshl_add_u64 v[2:3], s[20:21], 0, v[2:3]
	s_lshl_b32 s4, s30, 1
	v_lshl_add_u64 v[2:3], v[2:3], 0, s[4:5]
	v_lshlrev_b32_e32 v0, 1, v162
	v_lshl_add_u64 v[18:19], v[2:3], 0, v[0:1]
	global_load_dwordx4 v[58:61], v[18:19], off offset:160
	global_load_dwordx4 v[62:65], v[18:19], off offset:224
	global_load_dwordx4 v[66:69], v[18:19], off offset:128
	global_load_dwordx4 v[70:73], v[18:19], off offset:192
	global_load_dwordx4 v[2:5], v[164:165], off
	global_load_dwordx4 v[6:9], v[164:165], off offset:16
	global_load_dwordx4 v[10:13], v[164:165], off offset:64
	global_load_dwordx4 v[82:85], v[164:165], off offset:80
	global_load_dwordx4 v[86:89], v[164:165], off offset:128
	global_load_dwordx4 v[90:93], v[164:165], off offset:144
	global_load_dwordx4 v[94:97], v[164:165], off offset:192
	global_load_dwordx4 v[98:101], v[164:165], off offset:208
	global_load_dwordx4 v[102:105], v[164:165], off offset:256
	global_load_dwordx4 v[106:109], v[164:165], off offset:272
	global_load_dwordx4 v[50:53], v[18:19], off offset:32
	global_load_dwordx4 v[110:113], v[164:165], off offset:320
	global_load_dwordx4 v[114:117], v[164:165], off offset:336
	global_load_dwordx4 v[54:57], v[18:19], off offset:96
	global_load_dwordx4 v[118:121], v[164:165], off offset:384
	global_load_dwordx4 v[122:125], v[164:165], off offset:400
	global_load_dwordx4 v[126:129], v[164:165], off offset:448
	global_load_dwordx4 v[14:17], v[164:165], off offset:464
	global_load_dwordx4 v[74:77], v[18:19], off
	s_lshl_b32 s4, s0, 4
	s_add_i32 s31, s4, 0x8000
	v_ashrrev_i32_e32 v0, 1, v191
	s_movk_i32 s4, 0xffe0
	v_and_or_b32 v20, v0, s4, v162
	v_lshlrev_b32_e32 v0, 5, v21
	v_ashrrev_i32_e32 v21, 31, v20
	v_or_b32_e32 v22, 16, v20
	v_lshl_add_u64 v[20:21], v[20:21], 3, s[48:49]
	global_load_dwordx4 v[78:81], v[18:19], off offset:64
	global_load_dwordx4 v[30:33], v[20:21], off offset:48
	global_load_dwordx4 v[38:41], v[20:21], off offset:32
	global_load_dwordx4 v[42:45], v[20:21], off offset:16
	global_load_dwordx4 v[46:49], v[20:21], off
	s_movk_i32 s4, 0x7e0
	v_and_or_b32 v0, v0, s4, v162
	v_lshlrev_b32_e32 v195, 3, v0
	v_mov_b32_e32 v196, v245
	v_mov_b64_e32 v[244:245], v[242:243]
	v_mov_b64_e32 v[174:175], v[248:249]
	v_ashrrev_i32_e32 v23, 31, v22
	v_lshl_add_u64 v[34:35], v[22:23], 3, s[48:49]
	global_load_dwordx4 v[18:21], v[34:35], off offset:48
	global_load_dwordx4 v[22:25], v[34:35], off offset:32
	global_load_dwordx4 v[26:29], v[34:35], off offset:16
	s_nop 0
	global_load_dwordx4 v[34:37], v[34:35], off
	s_ashr_i32 s1, s0, 31
	s_lshl_b64 s[90:91], s[0:1], 14
	s_ashr_i32 s44, s31, 31
	s_lshl_b64 s[0:1], s[0:1], 23
	s_add_u32 s6, s42, s0
	s_addc_u32 s7, s43, s1
	s_add_u32 s8, s40, s0
	s_addc_u32 s9, s41, s1
	s_mov_b32 s4, s5
	s_mov_b32 s10, s5
	s_mov_b32 s11, s5
	s_mov_b32 s12, s5
	s_mov_b32 s13, s5
	s_mov_b32 s14, s5
	s_mov_b32 s15, s5
	s_mov_b32 s16, s5
	s_mov_b32 s17, s5
	s_mov_b32 s18, s5
	s_mov_b32 s19, s5
	s_mov_b32 s28, 1
	s_waitcnt vmcnt(0)
	v_lshlrev_b32_e32 v142, 16, v58
	v_and_b32_e32 v143, 0xffff0000, v58
	v_lshlrev_b32_e32 v226, 16, v66
	v_and_b32_e32 v227, 0xffff0000, v66
	v_lshlrev_b32_e32 v218, 16, v67
	v_and_b32_e32 v219, 0xffff0000, v67
	v_pk_mul_f32 v[66:67], v[226:227], v[226:227]
	v_pk_mul_f32 v[222:223], v[218:219], v[218:219]
	v_lshlrev_b32_e32 v214, 16, v68
	v_and_b32_e32 v215, 0xffff0000, v68
	v_lshlrev_b32_e32 v144, 16, v69
	v_and_b32_e32 v145, 0xffff0000, v69
	v_pk_mul_f32 v[68:69], v[214:215], v[214:215]
	v_pk_mul_f32 v[210:211], v[144:145], v[144:145]
	v_lshlrev_b32_e32 v202, 16, v51
	v_and_b32_e32 v203, 0xffff0000, v51
	v_lshlrev_b32_e32 v150, 16, v50
	v_and_b32_e32 v151, 0xffff0000, v50
	v_lshlrev_b32_e32 v238, 16, v52
	v_and_b32_e32 v239, 0xffff0000, v52
	v_lshlrev_b32_e32 v230, 16, v53
	v_and_b32_e32 v231, 0xffff0000, v53
	v_lshlrev_b32_e32 v158, 16, v74
	v_and_b32_e32 v159, 0xffff0000, v74
	v_lshlrev_b32_e32 v156, 16, v75
	v_and_b32_e32 v157, 0xffff0000, v75
	v_pk_mul_f32 v[50:51], v[158:159], v[158:159]
	v_lshlrev_b32_e32 v154, 16, v76
	v_add_f32_e32 v0, v50, v51
	v_pk_mul_f32 v[50:51], v[156:157], v[156:157]
	v_and_b32_e32 v155, 0xffff0000, v76
	v_add_f32_e32 v0, v50, v0
	v_add_f32_e32 v0, v51, v0
	v_pk_mul_f32 v[50:51], v[154:155], v[154:155]
	v_lshlrev_b32_e32 v152, 16, v77
	v_and_b32_e32 v153, 0xffff0000, v77
	v_add_f32_e32 v0, v50, v0
	v_add_f32_e32 v0, v51, v0
	v_pk_mul_f32 v[50:51], v[152:153], v[152:153]
	v_pk_mul_f32 v[52:53], v[238:239], v[238:239]
	v_add_f32_e32 v0, v50, v0
	v_add_f32_e32 v0, v51, v0
	v_pk_mul_f32 v[50:51], v[150:151], v[150:151]
	v_pk_mul_f32 v[234:235], v[230:231], v[230:231]
	v_add_f32_e32 v0, v50, v0
	v_add_f32_e32 v0, v51, v0
	v_pk_mul_f32 v[50:51], v[202:203], v[202:203]
	v_lshlrev_b32_e32 v242, 16, v78
	v_add_f32_e32 v0, v50, v0
	v_add_f32_e32 v0, v51, v0
	v_add_f32_e32 v0, v52, v0
	v_add_f32_e32 v0, v53, v0
	v_and_b32_e32 v243, 0xffff0000, v78
	v_add_f32_e32 v0, v234, v0
	v_lshlrev_b32_e32 v198, 16, v55
	v_and_b32_e32 v199, 0xffff0000, v55
	v_lshlrev_b32_e32 v200, 16, v54
	v_and_b32_e32 v201, 0xffff0000, v54
; __device__ __forceinline__ float lane_read(float v, int src) { return __int_as_float(__builtin_amdgcn_ds_bpermute(src << 2, __float_as_int(v))); }
; __device__ __forceinline__ void load_q_roped(const bf16_t* Qw, const float* __restrict__ wq, const float* __restrict__ RT, int pr, int pc, int hi, int lane, bf16x8 (&qr)[8]) {
;     ...
;   ss += lane_read(ss, lane ^ 32);
;   const float rstd = __builtin_amdgcn_rsqf(ss * (1.f / 128.f) + 1e-6f);
; #pragma unroll
;   for (int d0 = 0; d0 < 8; ++d0) { const f32x4 w0 = *(const f32x4*)(wq + d0 * 16), w1 = *(const f32x4*)(wq + d0 * 16 + 4);
; #pragma unroll
;     for (int e = 0; e < 8; ++e) y[d0][e] *= rstd * (e < 4 ? w0[e & 3] : w1[e & 3]); }
; #pragma unroll
;   for (int hf = 0; hf < 2; ++hf)
; #pragma unroll
;     for (int lo = 0; lo < 2; ++lo) { const int d0 = hf * 4 + lo;
;       const float* tp = RT + (size_t)((hf ? pc : pr) * 32 + lo * 16 + hi * 8) * 2;
;       f32x4 t[4];
; #pragma unroll
;       for (int q = 0; q < 4; ++q) t[q] = *(const f32x4*)(tp + 4 * q);
; #pragma unroll
;       for (int e = 0; e < 8; ++e) { const float cs = t[e >> 1][(e & 1) * 2], sn = t[e >> 1][(e & 1) * 2 + 1];
;         const float x1 = y[d0][e], x2 = y[d0 + 2][e]; y[d0][e] = x1 * cs - x2 * sn; y[d0 + 2][e] = x1 * sn + x2 * cs; } }
	v_add_f32_e32 v0, v235, v0
	v_pk_mul_f32 v[54:55], v[242:243], v[242:243]
	v_lshlrev_b32_e32 v248, 16, v79
	v_and_b32_e32 v249, 0xffff0000, v79
	v_add_f32_e32 v0, v54, v0
	v_add_f32_e32 v0, v55, v0
	v_pk_mul_f32 v[54:55], v[248:249], v[248:249]
	v_lshlrev_b32_e32 v206, 16, v80
	v_and_b32_e32 v207, 0xffff0000, v80
	v_add_f32_e32 v0, v54, v0
	v_add_f32_e32 v0, v55, v0
	v_pk_mul_f32 v[54:55], v[206:207], v[206:207]
	v_lshlrev_b32_e32 v204, 16, v81
	v_and_b32_e32 v205, 0xffff0000, v81
	v_add_f32_e32 v0, v54, v0
	v_add_f32_e32 v0, v55, v0
	v_pk_mul_f32 v[54:55], v[204:205], v[204:205]
	v_pk_mul_f32 v[52:53], v[200:201], v[200:201]
	v_add_f32_e32 v0, v54, v0
	v_add_f32_e32 v0, v55, v0
	v_add_f32_e32 v0, v52, v0
	v_pk_mul_f32 v[50:51], v[198:199], v[198:199]
	v_add_f32_e32 v0, v53, v0
	v_lshlrev_b32_e32 v240, 16, v56
	v_and_b32_e32 v241, 0xffff0000, v56
	v_add_f32_e32 v0, v50, v0
	v_lshlrev_b32_e32 v232, 16, v57
	v_and_b32_e32 v233, 0xffff0000, v57
	v_pk_mul_f32 v[56:57], v[240:241], v[240:241]
	v_add_f32_e32 v0, v51, v0
	v_add_f32_e32 v0, v56, v0
	v_pk_mul_f32 v[236:237], v[232:233], v[232:233]
	v_add_f32_e32 v0, v57, v0
	v_add_f32_e32 v0, v236, v0
	v_add_f32_e32 v0, v237, v0
	v_add_f32_e32 v0, v66, v0
	v_add_f32_e32 v0, v67, v0
	v_add_f32_e32 v0, v222, v0
	v_add_f32_e32 v0, v223, v0
	v_add_f32_e32 v0, v68, v0
	v_add_f32_e32 v0, v69, v0
	v_add_f32_e32 v0, v210, v0
	v_pk_mul_f32 v[168:169], v[142:143], v[142:143]
	v_add_f32_e32 v0, v211, v0
	v_lshlrev_b32_e32 v138, 16, v59
	v_and_b32_e32 v139, 0xffff0000, v59
	v_add_f32_e32 v0, v168, v0
	v_pk_mul_f32 v[148:149], v[138:139], v[138:139]
	v_add_f32_e32 v0, v169, v0
	v_lshlrev_b32_e32 v136, 16, v60
	v_and_b32_e32 v137, 0xffff0000, v60
	v_add_f32_e32 v0, v148, v0
	v_lshlrev_b32_e32 v140, 16, v63
	v_and_b32_e32 v141, 0xffff0000, v63
	v_lshlrev_b32_e32 v146, 16, v62
	v_and_b32_e32 v147, 0xffff0000, v62
	v_pk_mul_f32 v[62:63], v[136:137], v[136:137]
	v_add_f32_e32 v0, v149, v0
	v_lshlrev_b32_e32 v134, 16, v61
	v_and_b32_e32 v135, 0xffff0000, v61
	v_add_f32_e32 v0, v62, v0
	v_pk_mul_f32 v[58:59], v[134:135], v[134:135]
	v_add_f32_e32 v0, v63, v0
	v_lshlrev_b32_e32 v228, 16, v70
	v_and_b32_e32 v229, 0xffff0000, v70
	v_add_f32_e32 v0, v58, v0
	v_lshlrev_b32_e32 v220, 16, v71
	v_and_b32_e32 v221, 0xffff0000, v71
	v_pk_mul_f32 v[70:71], v[228:229], v[228:229]
	v_add_f32_e32 v0, v59, v0
	v_add_f32_e32 v0, v70, v0
	v_pk_mul_f32 v[224:225], v[220:221], v[220:221]
	v_add_f32_e32 v0, v71, v0
	v_lshlrev_b32_e32 v216, 16, v72
	v_and_b32_e32 v217, 0xffff0000, v72
	v_add_f32_e32 v0, v224, v0
	v_lshlrev_b32_e32 v192, 16, v73
	v_and_b32_e32 v193, 0xffff0000, v73
	v_pk_mul_f32 v[72:73], v[216:217], v[216:217]
	v_add_f32_e32 v0, v225, v0
	v_add_f32_e32 v0, v72, v0
	v_pk_mul_f32 v[212:213], v[192:193], v[192:193]
	v_add_f32_e32 v0, v73, v0
	v_add_f32_e32 v0, v212, v0
	v_pk_mul_f32 v[170:171], v[146:147], v[146:147]
	v_add_f32_e32 v0, v213, v0
	v_add_f32_e32 v0, v170, v0
	v_pk_mul_f32 v[160:161], v[140:141], v[140:141]
	v_add_f32_e32 v0, v171, v0
	v_lshlrev_b32_e32 v132, 16, v64
	v_and_b32_e32 v133, 0xffff0000, v64
	v_add_f32_e32 v0, v160, v0
	v_lshlrev_b32_e32 v130, 16, v65
	v_and_b32_e32 v131, 0xffff0000, v65
	v_pk_mul_f32 v[64:65], v[132:133], v[132:133]
	v_add_f32_e32 v0, v161, v0
	v_add_f32_e32 v0, v64, v0
	v_pk_mul_f32 v[60:61], v[130:131], v[130:131]
	v_add_f32_e32 v0, v65, v0
	v_add_f32_e32 v0, v60, v0
	v_add_f32_e32 v0, v61, v0
	ds_bpermute_b32 v50, v252, v0
	global_load_dwordx4 v[66:69], v195, s[48:49] offset:48
	global_load_dwordx4 v[70:73], v195, s[48:49] offset:32
	global_load_dwordx4 v[74:77], v195, s[48:49] offset:16
	global_load_dwordx4 v[78:81], v195, s[48:49]
	v_add_u32_e32 v168, 0, v176
	v_add_u32_e32 v169, 0, v177
	v_lshl_add_u64 v[170:171], s[40:41], 0, v[166:167]
	s_waitcnt lgkmcnt(0)
	v_add_f32_e32 v0, v0, v50
	v_mov_b32_e32 v50, 0x358637bd
	v_fmamk_f32 v0, v0, 0x3c000000, v50
	v_rsq_f32_e32 v0, v0
	global_load_dwordx4 v[50:53], v195, s[48:49] offset:176
	global_load_dwordx4 v[54:57], v195, s[48:49] offset:160
	global_load_dwordx4 v[58:61], v195, s[48:49] offset:144
	global_load_dwordx4 v[62:65], v195, s[48:49] offset:128
	v_pk_mul_f32 v[14:15], v[14:15], v[0:1] op_sel_hi:[1,0]
	v_pk_mul_f32 v[126:127], v[126:127], v[0:1] op_sel_hi:[1,0]
	v_pk_mul_f32 v[116:117], v[116:117], v[0:1] op_sel_hi:[1,0]
	v_pk_mul_f32 v[86:87], v[86:87], v[0:1] op_sel_hi:[1,0]
	v_pk_mul_f32 v[14:15], v[14:15], v[132:133]
	v_pk_mul_f32 v[132:133], v[126:127], v[146:147]
	v_pk_mul_f32 v[126:127], v[116:117], v[134:135]
	v_pk_mul_f32 v[114:115], v[114:115], v[0:1] op_sel_hi:[1,0]
	v_pk_mul_f32 v[112:113], v[112:113], v[0:1] op_sel_hi:[1,0]
	v_pk_mul_f32 v[90:91], v[90:91], v[0:1] op_sel_hi:[1,0]
	v_pk_mul_f32 v[116:117], v[86:87], v[242:243]
	v_lshl_add_u64 v[86:87], s[6:7], 0, v[166:167]
	v_pk_mul_f32 v[134:135], v[114:115], v[136:137]
	v_pk_mul_f32 v[136:137], v[112:113], v[138:139]
	v_pk_mul_f32 v[110:111], v[110:111], v[0:1] op_sel_hi:[1,0]
	v_pk_mul_f32 v[108:109], v[108:109], v[0:1] op_sel_hi:[1,0]
	v_pk_mul_f32 v[106:107], v[106:107], v[0:1] op_sel_hi:[1,0]
	v_pk_mul_f32 v[112:113], v[90:91], v[206:207]
	v_add_co_u32_e32 v90, vcc, s37, v86
	v_pk_mul_f32 v[138:139], v[110:111], v[142:143]
	v_pk_mul_f32 v[142:143], v[108:109], v[144:145]
	v_pk_mul_f32 v[144:145], v[106:107], v[214:215]
	v_pk_mul_f32 v[104:105], v[104:105], v[0:1] op_sel_hi:[1,0]
	v_pk_mul_f32 v[102:103], v[102:103], v[0:1] op_sel_hi:[1,0]
	v_pk_mul_f32 v[92:93], v[92:93], v[0:1] op_sel_hi:[1,0]
	v_pk_mul_f32 v[88:89], v[88:89], v[0:1] op_sel_hi:[1,0]
	v_addc_co_u32_e32 v91, vcc, 0, v87, vcc
	v_lshl_add_u64 v[106:107], s[8:9], 0, v[184:185]
; #define SLOAD(i, t) do { const long rb_ = TROW(t); const char* vt_ = (const char*)Vh + rb_ * (LDK * 2); const char* kt_ = (const char*)Kh + rb_ * (LDK * 2); \
;     sr_[i].vs0 = *(const bf16x8*)(vt_ + lo0); sr_[i].vs1 = *(const bf16x8*)(vt_ + lo0 + 32 * LDK * 2); \
;     sr_[i].ks0 = *(const bf16x8*)(kt_ + lo0); sr_[i].ks1 = *(const bf16x8*)(kt_ + lo0 + 32 * LDK * 2); } while (0)
; #define SWRITE(bb, i) do { *(bf16x8*)((char*)V_lds + (bb) * SHM_V + vst0) = sr_[i].vs0;          \
;     *(bf16x8*)((char*)V_lds + (bb) * SHM_V + vst1) = sr_[i].vs1; int kc = sc * 2;               \
;     *(bf16x8*)((char*)K_lds + (bb) * SHM_K + KSWZ(sr, kc)) = sr_[i].ks0;                       \
;     *(bf16x8*)((char*)K_lds + (bb) * SHM_K + KSWZ(32 + sr, kc)) = sr_[i].ks1; } while (0)
; __device__ __forceinline__ void load_q_roped(const bf16_t* Qw, const float* __restrict__ wq, const float* __restrict__ RT, int pr, int pc, int hi, int lane, bf16x8 (&qr)[8]) {
;     ...
;       for (int e = 0; e < 8; ++e) { const float cs = t[e >> 1][(e & 1) * 2], sn = t[e >> 1][(e & 1) * 2 + 1];
;         const float x1 = y[d0][e], x2 = y[d0 + 2][e]; y[d0][e] = x1 * cs - x2 * sn; y[d0 + 2][e] = x1 * sn + x2 * cs; } }
; template <bool META>
; __device__ __forceinline__ void attn_unit(const bf16_t* Q, bf16_t* Oo, const bf16_t* __restrict__ Kb, const bf16_t* __restrict__ Vb, int b, int kvh, int h, int qb, char* lds, const int tid, const float* qn, const float* RT) {
;     ...
;   f32x16 pA0, pA1, pB0, pB1; float mnA, mnB, alA, alB; bf16x8 pa0, pa1, pa2, pa3;
;   constexpr int SE = 0, SO = 0;
;   SLOAD(SE, 0); asm volatile("s_waitcnt vmcnt(0)" ::: "memory"); SWRITE(0, SE); __syncthreads();
	v_pk_mul_f32 v[146:147], v[104:105], v[218:219]
	v_pk_mul_f32 v[148:149], v[102:103], v[226:227]
	v_pk_mul_f32 v[110:111], v[92:93], v[204:205]
	v_pk_mul_f32 v[114:115], v[88:89], v[248:249]
	global_load_dwordx4 v[86:89], v[86:87], off
	s_nop 0
	global_load_dwordx4 v[90:93], v[90:91], off
	v_pk_mul_f32 v[128:129], v[128:129], v[0:1] op_sel_hi:[1,0]
	global_load_dwordx4 v[102:105], v[106:107], off
	v_add_co_u32_e32 v106, vcc, s37, v106
	v_pk_mul_f32 v[120:121], v[120:121], v[0:1] op_sel_hi:[1,0]
	s_nop 0
	v_addc_co_u32_e32 v107, vcc, 0, v107, vcc
	global_load_dwordx4 v[106:109], v[106:107], off
	v_pk_mul_f32 v[2:3], v[2:3], v[0:1] op_sel_hi:[1,0]
	v_pk_mul_f32 v[128:129], v[128:129], v[140:141]
	v_pk_mul_f32 v[140:141], v[120:121], v[220:221]
	v_pk_mul_f32 v[120:121], v[2:3], v[158:159]
	v_pk_mul_f32 v[2:3], v[16:17], v[0:1] op_sel_hi:[1,0]
	v_mov_b32_e32 v17, v48
	v_mov_b32_e32 v48, v47
	v_mov_b32_e32 v16, v46
	v_pk_mul_f32 v[46:47], v[48:49], v[116:117]
	v_pk_mul_f32 v[4:5], v[4:5], v[0:1] op_sel_hi:[1,0]
	v_pk_fma_f32 v[46:47], v[16:17], v[120:121], v[46:47] neg_lo:[0,0,1] neg_hi:[0,0,1]
	v_pk_mul_f32 v[16:17], v[16:17], v[116:117]
	v_pk_mul_f32 v[4:5], v[4:5], v[156:157]
	v_pk_fma_f32 v[16:17], v[48:49], v[120:121], v[16:17]
	v_mov_b32_e32 v49, v44
	v_mov_b32_e32 v44, v43
	v_mov_b32_e32 v48, v42
	v_pk_mul_f32 v[42:43], v[44:45], v[114:115]
	v_pk_mul_f32 v[6:7], v[6:7], v[0:1] op_sel_hi:[1,0]
	v_pk_fma_f32 v[42:43], v[48:49], v[4:5], v[42:43] neg_lo:[0,0,1] neg_hi:[0,0,1]
	v_pk_mul_f32 v[48:49], v[48:49], v[114:115]
	v_pk_mul_f32 v[6:7], v[6:7], v[154:155]
	v_pk_fma_f32 v[114:115], v[44:45], v[4:5], v[48:49]
	v_mov_b32_e32 v5, v40
	v_mov_b32_e32 v40, v39
	v_mov_b32_e32 v4, v38
	v_pk_mul_f32 v[38:39], v[40:41], v[112:113]
	v_pk_mul_f32 v[8:9], v[8:9], v[0:1] op_sel_hi:[1,0]
	v_pk_fma_f32 v[38:39], v[4:5], v[6:7], v[38:39] neg_lo:[0,0,1] neg_hi:[0,0,1]
	v_pk_mul_f32 v[4:5], v[4:5], v[112:113]
	v_pk_mul_f32 v[8:9], v[8:9], v[152:153]
	v_pk_fma_f32 v[112:113], v[40:41], v[6:7], v[4:5]
	v_mov_b32_e32 v5, v32
	v_mov_b32_e32 v32, v31
	v_mov_b32_e32 v4, v30
	v_pk_mul_f32 v[6:7], v[32:33], v[110:111]
	v_pk_mul_f32 v[94:95], v[94:95], v[0:1] op_sel_hi:[1,0]
	v_pk_fma_f32 v[30:31], v[4:5], v[8:9], v[6:7] neg_lo:[0,0,1] neg_hi:[0,0,1]
	v_pk_mul_f32 v[4:5], v[4:5], v[110:111]
	v_pk_mul_f32 v[94:95], v[94:95], v[200:201]
	v_pk_mul_f32 v[10:11], v[10:11], v[0:1] op_sel_hi:[1,0]
	v_pk_fma_f32 v[110:111], v[32:33], v[8:9], v[4:5]
	v_mov_b32_e32 v5, v36
	v_mov_b32_e32 v36, v35
	v_pk_mul_f32 v[10:11], v[10:11], v[150:151]
	v_mov_b32_e32 v4, v34
	v_pk_mul_f32 v[6:7], v[36:37], v[94:95]
	v_pk_mul_f32 v[96:97], v[96:97], v[0:1] op_sel_hi:[1,0]
	v_pk_fma_f32 v[116:117], v[4:5], v[10:11], v[6:7] neg_lo:[0,0,1] neg_hi:[0,0,1]
	v_pk_mul_f32 v[4:5], v[4:5], v[94:95]
	v_pk_mul_f32 v[96:97], v[96:97], v[198:199]
	v_pk_mul_f32 v[12:13], v[12:13], v[0:1] op_sel_hi:[1,0]
	v_pk_fma_f32 v[94:95], v[36:37], v[10:11], v[4:5]
	v_mov_b32_e32 v5, v28
	v_mov_b32_e32 v28, v27
	v_pk_mul_f32 v[12:13], v[12:13], v[202:203]
	v_mov_b32_e32 v4, v26
	v_pk_mul_f32 v[6:7], v[28:29], v[96:97]
	v_pk_mul_f32 v[98:99], v[98:99], v[0:1] op_sel_hi:[1,0]
	v_pk_fma_f32 v[120:121], v[4:5], v[12:13], v[6:7] neg_lo:[0,0,1] neg_hi:[0,0,1]
	v_pk_mul_f32 v[4:5], v[4:5], v[96:97]
	v_pk_mul_f32 v[98:99], v[98:99], v[240:241]
	v_pk_mul_f32 v[82:83], v[82:83], v[0:1] op_sel_hi:[1,0]
	v_pk_fma_f32 v[12:13], v[28:29], v[12:13], v[4:5]
	v_mov_b32_e32 v5, v24
	v_mov_b32_e32 v24, v23
	v_pk_mul_f32 v[82:83], v[82:83], v[238:239]
	v_mov_b32_e32 v4, v22
	v_pk_mul_f32 v[6:7], v[24:25], v[98:99]
	v_pk_mul_f32 v[100:101], v[100:101], v[0:1] op_sel_hi:[1,0]
	v_pk_fma_f32 v[96:97], v[4:5], v[82:83], v[6:7] neg_lo:[0,0,1] neg_hi:[0,0,1]
	v_pk_mul_f32 v[4:5], v[4:5], v[98:99]
	v_pk_mul_f32 v[124:125], v[124:125], v[0:1] op_sel_hi:[1,0]
	v_pk_mul_f32 v[122:123], v[122:123], v[0:1] op_sel_hi:[1,0]
	v_pk_mul_f32 v[118:119], v[118:119], v[0:1] op_sel_hi:[1,0]
	v_pk_mul_f32 v[100:101], v[100:101], v[232:233]
	v_pk_mul_f32 v[84:85], v[84:85], v[0:1] op_sel_hi:[1,0]
	v_pk_fma_f32 v[82:83], v[24:25], v[82:83], v[4:5]
	v_mov_b32_e32 v5, v20
	v_mov_b32_e32 v20, v19
	v_add_u32_e32 v0, 0, v179
	v_pk_mul_f32 v[84:85], v[84:85], v[230:231]
	v_mov_b32_e32 v4, v18
	v_pk_mul_f32 v[6:7], v[20:21], v[100:101]
	s_waitcnt vmcnt(0)
	s_waitcnt vmcnt(3)
	ds_write_b128 v168, v[86:89]
	s_waitcnt vmcnt(2)
	ds_write_b128 v169, v[90:93]
	s_waitcnt vmcnt(1)
	ds_write_b128 v0, v[102:105] offset:49152
	v_add_u32_e32 v0, 0, v180
	v_pk_mul_f32 v[2:3], v[2:3], v[130:131]
	v_pk_fma_f32 v[130:131], v[4:5], v[84:85], v[6:7] neg_lo:[0,0,1] neg_hi:[0,0,1]
	v_pk_mul_f32 v[4:5], v[4:5], v[100:101]
	s_waitcnt vmcnt(0)
	ds_write_b128 v0, v[106:109] offset:49152
	v_add_u32_e32 v0, 0, v182
	v_pk_fma_f32 v[84:85], v[20:21], v[84:85], v[4:5]
	s_waitcnt lgkmcnt(0)
	s_barrier
; __device__ __forceinline__ unsigned cvtpk(float lo, float hi) { const f32x2c v = {lo, hi}; const bf16x2c r = __builtin_convertvector(v, bf16x2c); return __builtin_bit_cast(unsigned, r); }
; __device__ __forceinline__ void qkt(f32x16& p0, f32x16& p1, const bf16_t* Ks, const bf16x8* qr, int r32, int hi) {
;   p0 = f32x16{}; p1 = f32x16{};
; #pragma unroll
;   for (int d0 = 0; d0 < 8; ++d0) { int cb = (d0 * 16 + hi * 8) * 2;
;     bf16x8 b0 = *reinterpret_cast<const bf16x8*>((const char*)Ks + KSWZ(r32, cb));
;     bf16x8 b1 = *reinterpret_cast<const bf16x8*>((const char*)Ks + KSWZ(32 + r32, cb));
;     p0 = __builtin_amdgcn_mfma_f32_32x32x16_bf16(b0, qr[d0], p0, 0, 0, 0);
;     p1 = __builtin_amdgcn_mfma_f32_32x32x16_bf16(b1, qr[d0], p1, 0, 0, 0); }
; }
; __device__ __forceinline__ void load_q_roped(const bf16_t* Qw, const float* __restrict__ wq, const float* __restrict__ RT, int pr, int pc, int hi, int lane, bf16x8 (&qr)[8]) {
;     ...
; #pragma unroll
;   for (int d0 = 0; d0 < 8; ++d0) { u32x4 w; w.x = cvtpk(y[d0][0], y[d0][1]); w.y = cvtpk(y[d0][2], y[d0][3]); w.z = cvtpk(y[d0][4], y[d0][5]); w.w = cvtpk(y[d0][6], y[d0][7]);
;     qr[d0] = *reinterpret_cast<bf16x8*>(&w); }
	ds_read_b128 v[4:7], v0 offset:49152
	v_pk_mul_f32 v[118:119], v[118:119], v[228:229]
	v_mov_b32_e32 v9, v80
	v_mov_b32_e32 v80, v79
	v_mov_b32_e32 v8, v78
	v_pk_mul_f32 v[10:11], v[80:81], v[118:119]
	v_cvt_pk_bf16_f32 v98, v46, v47
	v_cvt_pk_bf16_f32 v99, v42, v43
	v_cvt_pk_bf16_f32 v100, v38, v39
	v_cvt_pk_bf16_f32 v101, v30, v31
	v_mov_b32_e32 v89, v76
	v_mov_b32_e32 v76, v75
	v_pk_fma_f32 v[78:79], v[8:9], v[148:149], v[10:11] neg_lo:[0,0,1] neg_hi:[0,0,1]
	v_pk_mul_f32 v[86:87], v[8:9], v[118:119]
	ds_read_b128 v[8:11], v0 offset:50176
	s_waitcnt lgkmcnt(1)
	v_mfma_f32_32x32x16_bf16 v[18:33], v[4:7], v[98:101], 0
	v_mov_b32_e32 v88, v74
	v_mul_f32_e64 v4, v76, v140
	v_mul_f32_e64 v5, v77, v141
	v_add_u32_e32 v0, 0, v182
	v_fma_f32 v74, v88, v146, -v4
	v_fma_f32 v75, v89, v147, -v5
	ds_read_b128 v[4:7], v0 offset:51200
	v_pk_mul_f32 v[122:123], v[122:123], v[216:217]
	v_mov_b32_e32 v91, v72
	v_cvt_pk_bf16_f32 v102, v116, v117
	v_cvt_pk_bf16_f32 v103, v120, v121
	v_cvt_pk_bf16_f32 v104, v96, v97
	v_cvt_pk_bf16_f32 v105, v130, v131
	v_mov_b32_e32 v72, v71
	s_waitcnt lgkmcnt(1)
	v_mfma_f32_32x32x16_bf16 v[34:49], v[8:11], v[98:101], 0
	v_mov_b32_e32 v90, v70
	ds_read_b128 v[8:11], v0 offset:52224
	v_add_u32_e32 v0, 0, v182
	v_cvt_pk_bf16_f32 v106, v16, v17
	v_cvt_pk_bf16_f32 v107, v114, v115
	v_cvt_pk_bf16_f32 v108, v112, v113
	v_cvt_pk_bf16_f32 v109, v110, v111
	s_waitcnt lgkmcnt(1)
	v_mfma_f32_32x32x16_bf16 v[18:33], v[4:7], v[102:105], v[18:33]
	v_mul_f32_e64 v4, v72, v122
	v_mul_f32_e64 v5, v73, v123
	v_cvt_pk_bf16_f32 v110, v94, v95
	v_fma_f32 v70, v90, v144, -v4
	v_fma_f32 v71, v91, v145, -v5
	ds_read_b128 v[4:7], v0 offset:53248
	v_cvt_pk_bf16_f32 v111, v12, v13
	v_cvt_pk_bf16_f32 v112, v82, v83
	v_cvt_pk_bf16_f32 v113, v84, v85
	s_waitcnt lgkmcnt(1)
	v_mfma_f32_32x32x16_bf16 v[34:49], v[8:11], v[102:105], v[34:49]
	ds_read_b128 v[8:11], v0 offset:54272
	v_add_u32_e32 v0, 0, v182
	v_mov_b32_e32 v97, v60
	v_mov_b32_e32 v60, v59
	v_mov_b32_e32 v96, v58
	v_pk_mul_f32 v[124:125], v[124:125], v[192:193]
	v_mov_b32_e32 v93, v68
	s_waitcnt lgkmcnt(1)
	v_mfma_f32_32x32x16_bf16 v[18:33], v[4:7], v[106:109], v[18:33]
	ds_read_b128 v[4:7], v0 offset:55296
	v_mov_b32_e32 v68, v67
	v_mov_b32_e32 v92, v66
	v_mul_f32_e64 v66, v68, v124
	v_mul_f32_e64 v67, v69, v125
	v_mov_b32_e32 v59, v56
	v_pk_fma_f32 v[16:17], v[92:93], v[142:143], v[66:67] neg_lo:[0,0,1] neg_hi:[0,0,1]
	v_mov_b32_e32 v56, v55
	s_waitcnt lgkmcnt(1)
	v_mfma_f32_32x32x16_bf16 v[34:49], v[8:11], v[106:109], v[34:49]
	ds_read_b128 v[8:11], v0 offset:56320
	v_add_u32_e32 v0, 0, v182
	v_cvt_pk_bf16_f32 v114, v78, v79
	v_cvt_pk_bf16_f32 v115, v74, v75
	v_cvt_pk_bf16_f32 v116, v70, v71
	v_cvt_pk_bf16_f32 v117, v16, v17
	v_mov_b32_e32 v58, v54
	s_waitcnt lgkmcnt(1)
	v_mfma_f32_32x32x16_bf16 v[18:33], v[4:7], v[110:113], v[18:33]
	v_mul_f32_e64 v4, v60, v128
	v_mul_f32_e64 v5, v61, v129
	v_mov_b32_e32 v67, v64
	v_fma_f32 v12, v96, v136, -v4
	v_fma_f32 v13, v97, v137, -v5
	ds_read_b128 v[4:7], v0 offset:57344
	v_mov_b32_e32 v64, v63
	v_mov_b32_e32 v55, v52
	v_mov_b32_e32 v52, v51
	s_waitcnt lgkmcnt(1)
	v_mfma_f32_32x32x16_bf16 v[34:49], v[8:11], v[110:113], v[34:49]
	ds_read_b128 v[8:11], v0 offset:58368
	v_add_u32_e32 v0, 0, v182
	v_mov_b32_e32 v66, v62
	v_mul_f32_e64 v62, v64, v132
	v_mul_f32_e64 v63, v65, v133
	v_mov_b32_e32 v54, v50
	v_pk_fma_f32 v[62:63], v[66:67], v[138:139], v[62:63] neg_lo:[0,0,1] neg_hi:[0,0,1]
	v_cvt_pk_bf16_f32 v119, v12, v13
	s_waitcnt lgkmcnt(1)
	v_mfma_f32_32x32x16_bf16 v[18:33], v[4:7], v[114:117], v[18:33]
	v_mul_f32_e64 v4, v56, v14
	v_mul_f32_e64 v5, v57, v15
	v_cvt_pk_bf16_f32 v118, v62, v63
	v_fma_f32 v16, v58, v134, -v4
	v_fma_f32 v17, v59, v135, -v5
	ds_read_b128 v[4:7], v0 offset:59392
	v_cvt_pk_bf16_f32 v120, v16, v17
	v_pk_fma_f32 v[12:13], v[80:81], v[148:149], v[86:87]
	v_pk_mul_f32 v[14:15], v[58:59], v[14:15]
	s_waitcnt lgkmcnt(1)
	v_mfma_f32_32x32x16_bf16 v[34:49], v[8:11], v[114:117], v[34:49]
	v_mul_f32_e64 v8, v52, v2
	v_mul_f32_e64 v9, v53, v3
	v_mul_f32_e64 v2, v54, v2
	v_mul_f32_e64 v3, v55, v3
	v_fma_f32 v8, v54, v126, -v8
	v_fma_f32 v9, v55, v127, -v9
	v_pk_fma_f32 v[2:3], v[52:53], v[126:127], v[2:3]
	v_cvt_pk_bf16_f32 v121, v8, v9
	ds_read_b128 v[8:11], v0 offset:60416
	v_add_u32_e32 v0, 0, v182
	s_waitcnt lgkmcnt(1)
	v_mfma_f32_32x32x16_bf16 v[18:33], v[4:7], v[118:121], v[18:33]
	v_mul_f32_e64 v4, v88, v140
	v_mul_f32_e64 v5, v89, v141
	v_mov_b64_e32 v[248:249], v[174:175]
	v_fma_f32 v16, v76, v146, v4
	v_fma_f32 v17, v77, v147, v5
	v_pk_mul_f32 v[4:5], v[90:91], v[122:123]
	v_cvt_pk_bf16_f32 v122, v12, v13
	v_pk_fma_f32 v[50:51], v[72:73], v[144:145], v[4:5]
	ds_read_b128 v[4:7], v0 offset:61440
	s_waitcnt lgkmcnt(1)
	v_mfma_f32_32x32x16_bf16 v[34:49], v[8:11], v[118:121], v[34:49]
	v_mul_f32_e64 v8, v92, v124
	v_mul_f32_e64 v9, v93, v125
	v_cvt_pk_bf16_f32 v123, v16, v17
	v_fma_f32 v8, v68, v142, v8
	v_fma_f32 v9, v69, v143, v9
	v_cvt_pk_bf16_f32 v124, v50, v51
	v_cvt_pk_bf16_f32 v125, v8, v9
	ds_read_b128 v[8:11], v0 offset:62464
	v_add_u32_e32 v0, 0, v182
	s_waitcnt lgkmcnt(1)
	v_mfma_f32_32x32x16_bf16 v[18:33], v[4:7], v[122:125], v[18:33]
	v_mul_f32_e64 v4, v66, v132
	v_mul_f32_e64 v5, v67, v133
	v_mov_b64_e32 v[242:243], v[244:245]
	v_fma_f32 v12, v64, v138, v4
	v_fma_f32 v13, v65, v139, v5
	v_pk_mul_f32 v[4:5], v[96:97], v[128:129]
	v_cvt_pk_bf16_f32 v126, v12, v13
	v_pk_fma_f32 v[16:17], v[60:61], v[136:137], v[4:5]
	ds_read_b128 v[4:7], v0 offset:63488
	s_waitcnt lgkmcnt(1)
; #define SLOAD(i, t) do { const long rb_ = TROW(t); const char* vt_ = (const char*)Vh + rb_ * (LDK * 2); const char* kt_ = (const char*)Kh + rb_ * (LDK * 2); \
;     sr_[i].vs0 = *(const bf16x8*)(vt_ + lo0); sr_[i].vs1 = *(const bf16x8*)(vt_ + lo0 + 32 * LDK * 2); \
;     sr_[i].ks0 = *(const bf16x8*)(kt_ + lo0); sr_[i].ks1 = *(const bf16x8*)(kt_ + lo0 + 32 * LDK * 2); } while (0)
; #define SWRITE(bb, i) do { *(bf16x8*)((char*)V_lds + (bb) * SHM_V + vst0) = sr_[i].vs0;          \
;     *(bf16x8*)((char*)V_lds + (bb) * SHM_V + vst1) = sr_[i].vs1; int kc = sc * 2;               \
;     *(bf16x8*)((char*)K_lds + (bb) * SHM_K + KSWZ(sr, kc)) = sr_[i].ks0;                       \
;     *(bf16x8*)((char*)K_lds + (bb) * SHM_K + KSWZ(32 + sr, kc)) = sr_[i].ks1; } while (0)
; #define SWAIT() asm volatile("s_waitcnt vmcnt(0)" ::: "memory")
; __device__ __forceinline__ void partialSM(f32x16& p0, f32x16& p1, float& m_reg, float& mn, float& alpha) {
;   constexpr float C = ASCALE * 1.4426950408889634f;
;   float pmax = p0[0];
; #pragma unroll
;   for (int r = 1; r < 16; ++r) pmax = fmaxf(pmax, p0[r]);
; #pragma unroll
;   for (int r = 0; r < 16; ++r) pmax = fmaxf(pmax, p1[r]);
;   { auto rr = __builtin_amdgcn_permlane32_swap(__float_as_uint(pmax), __float_as_uint(pmax), false, false);
;     pmax = fmaxf(__uint_as_float(rr[0]), __uint_as_float(rr[1])); }
;   if (__builtin_expect(__all(pmax - m_reg <= ATHR / ASCALE), 1)) { mn = m_reg; alpha = 1.f; }
;   else { mn = fmaxf(m_reg, pmax); alpha = __builtin_amdgcn_exp2f((m_reg - mn) * C); m_reg = mn; }
;   float mnC = -mn * C;
; #pragma unroll
;   for (int r = 0; r < 16; ++r) p0[r] = fmaf(p0[r], C, mnC);
; #pragma unroll
;   for (int r = 0; r < 16; ++r) p1[r] = fmaf(p1[r], C, mnC);
; #pragma unroll
;   for (int r = 0; r < 16; ++r) p0[r] = __builtin_amdgcn_exp2f(p0[r]);
; }
; template <bool META>
; __device__ __forceinline__ void attn_unit(const bf16_t* Q, bf16_t* Oo, const bf16_t* __restrict__ Kb, const bf16_t* __restrict__ Vb, int b, int kvh, int h, int qb, char* lds, const int tid, const float* qn, const float* RT) {
;     ...
;   SLOAD(SE, 0); asm volatile("s_waitcnt vmcnt(0)" ::: "memory"); SWRITE(0, SE); __syncthreads();
;   qkt(pA0, pA1, K_lds, qr, r32, hi); partialSM(pA0, pA1, m_reg, mnA, alA);
;   SLOAD(SO, 1);
;   SWAIT(); SWRITE(1, SO); __syncthreads();
	v_mfma_f32_32x32x16_bf16 v[34:49], v[8:11], v[122:125], v[34:49]
	v_fma_f32 v8, v56, v134, v14
	v_fma_f32 v9, v57, v135, v15
	v_cvt_pk_bf16_f32 v127, v16, v17
	v_cvt_pk_bf16_f32 v128, v8, v9
	v_cvt_pk_bf16_f32 v129, v2, v3
	ds_read_b128 v[8:11], v0 offset:64512
	v_mov_b32_e32 v245, v196
	s_waitcnt lgkmcnt(1)
	v_mfma_f32_32x32x16_bf16 v[18:33], v[4:7], v[126:129], v[18:33]
	s_waitcnt lgkmcnt(0)
	v_mfma_f32_32x32x16_bf16 v[34:49], v[8:11], v[126:129], v[34:49]
	s_nop 9
	v_max_f32_e32 v0, v19, v19
	v_max_f32_e32 v2, v18, v18
	v_max_f32_e32 v0, v2, v0
	v_max3_f32 v0, v0, v20, v21
	v_max3_f32 v0, v0, v22, v23
	v_max3_f32 v0, v0, v24, v25
	v_max3_f32 v0, v0, v26, v27
	v_max3_f32 v0, v0, v28, v29
	v_max3_f32 v0, v0, v30, v31
	v_max3_f32 v0, v0, v32, v33
	v_max3_f32 v0, v0, v34, v35
	v_max3_f32 v0, v0, v36, v37
	v_max3_f32 v0, v0, v38, v39
	v_max3_f32 v0, v0, v40, v41
	v_max3_f32 v0, v0, v42, v43
	v_max3_f32 v0, v0, v44, v45
	v_max3_f32 v0, v0, v46, v47
	v_max3_f32 v0, v0, v48, v49
	v_mov_b32_e32 v2, v0
	s_nop 1
	v_permlane32_swap_b32_e32 v0, v2
	v_max_f32_e32 v2, v2, v2
	v_max_f32_e32 v0, v0, v0
	v_max_f32_e32 v0, v0, v2
	v_add_f32_e32 v2, 0x7149f2ca, v0
	v_cmp_ge_f32_e32 vcc, s25, v2
	s_cmp_eq_u64 vcc, exec
	s_cselect_b64 vcc, -1, 0
	s_bitset1_b32 s0, 15
	s_add_u32 s6, s42, s0
	s_addc_u32 s7, s43, s1
	s_add_u32 s8, s40, s0
	v_lshl_add_u64 v[2:3], s[6:7], 0, v[166:167]
	s_addc_u32 s9, s41, s1
	v_add_co_u32_e64 v4, s[0:1], s37, v2
	v_max_f32_e32 v0, 0xf149f2ca, v0
	s_nop 0
	v_addc_co_u32_e64 v5, s[0:1], 0, v3, s[0:1]
	global_load_dwordx4 v[50:53], v[2:3], off
	global_load_dwordx4 v[54:57], v[4:5], off
	v_lshl_add_u64 v[2:3], s[8:9], 0, v[184:185]
	global_load_dwordx4 v[58:61], v[2:3], off
	v_add_co_u32_e64 v2, s[0:1], s37, v2
	v_cndmask_b32_e32 v150, v0, v246, vcc
	s_nop 0
	v_addc_co_u32_e64 v3, s[0:1], 0, v3, s[0:1]
	global_load_dwordx4 v[62:65], v[2:3], off
	v_sub_f32_e32 v2, 0xf149f2ca, v0
	v_mul_f32_e32 v2, 0x3e0293ee, v2
	v_exp_f32_e32 v66, v2
	v_mul_f32_e32 v0, 0xbe0293ee, v150
	v_fmamk_f32 v18, v18, 0x3e0293ee, v0
	v_fmamk_f32 v19, v19, 0x3e0293ee, v0
	v_cndmask_b32_e64 v192, v66, 1.0, vcc
	v_mov_b32_e32 v66, v0
	v_fmamk_f32 v20, v20, 0x3e0293ee, v0
	v_fmamk_f32 v21, v21, 0x3e0293ee, v0
	v_fmamk_f32 v22, v22, 0x3e0293ee, v0
	v_fmamk_f32 v23, v23, 0x3e0293ee, v0
	v_fmamk_f32 v24, v24, 0x3e0293ee, v0
	v_fmamk_f32 v25, v25, 0x3e0293ee, v0
	v_fmamk_f32 v26, v26, 0x3e0293ee, v0
	v_fmamk_f32 v27, v27, 0x3e0293ee, v0
	v_fmamk_f32 v28, v28, 0x3e0293ee, v0
	v_fmamk_f32 v29, v29, 0x3e0293ee, v0
	v_fmamk_f32 v30, v30, 0x3e0293ee, v0
	v_fmamk_f32 v31, v31, 0x3e0293ee, v0
	v_fmamk_f32 v32, v32, 0x3e0293ee, v0
	v_fmac_f32_e32 v66, 0x3e0293ee, v33
	s_add_i32 s0, 0, 0x10000
	s_mov_b32 s6, s5
	s_mov_b32 s7, s5
	s_mov_b32 s8, s5
	s_mov_b32 s9, s5
	v_mov_b64_e32 v[2:3], s[4:5]
	v_pk_fma_f32 v[130:131], v[48:49], s[36:37], v[0:1] op_sel_hi:[1,0,0]
	v_pk_fma_f32 v[132:133], v[46:47], s[36:37], v[0:1] op_sel_hi:[1,0,0]
	v_pk_fma_f32 v[134:135], v[44:45], s[36:37], v[0:1] op_sel_hi:[1,0,0]
	v_pk_fma_f32 v[136:137], v[42:43], s[36:37], v[0:1] op_sel_hi:[1,0,0]
	v_pk_fma_f32 v[138:139], v[40:41], s[36:37], v[0:1] op_sel_hi:[1,0,0]
	v_pk_fma_f32 v[140:141], v[38:39], s[36:37], v[0:1] op_sel_hi:[1,0,0]
	v_pk_fma_f32 v[142:143], v[36:37], s[36:37], v[0:1] op_sel_hi:[1,0,0]
	v_pk_fma_f32 v[144:145], v[34:35], s[36:37], v[0:1] op_sel_hi:[1,0,0]
	v_exp_f32_e32 v146, v18
	v_exp_f32_e32 v147, v19
	v_exp_f32_e32 v148, v20
	v_exp_f32_e32 v159, v21
	v_exp_f32_e32 v160, v22
	v_exp_f32_e32 v209, v23
	v_exp_f32_e32 v149, v24
	v_exp_f32_e32 v161, v25
	v_exp_f32_e32 v151, v26
	v_exp_f32_e32 v153, v27
	v_exp_f32_e32 v154, v28
	v_exp_f32_e32 v157, v29
	v_exp_f32_e32 v152, v30
	v_exp_f32_e32 v155, v31
	v_exp_f32_e32 v156, v32
	v_exp_f32_e32 v158, v66
	v_add_u32_e32 v0, s0, v179
	v_mov_b64_e32 v[16:17], s[18:19]
	s_waitcnt vmcnt(0)
	s_waitcnt vmcnt(3)
	ds_write_b128 v168, v[50:53] offset:16384
	s_waitcnt vmcnt(2)
	ds_write_b128 v169, v[54:57] offset:16384
	v_mov_b64_e32 v[4:5], s[6:7]
	s_waitcnt vmcnt(1)
	ds_write_b128 v0, v[58:61]
	v_add_u32_e32 v0, s0, v180
	v_mov_b64_e32 v[6:7], s[8:9]
	v_mov_b64_e32 v[8:9], s[10:11]
	v_mov_b64_e32 v[10:11], s[12:13]
	v_mov_b64_e32 v[12:13], s[14:15]
	v_mov_b64_e32 v[14:15], s[16:17]
	s_waitcnt vmcnt(0)
	ds_write_b128 v0, v[62:65]
	v_mov_b64_e32 v[64:65], v[16:17]
	v_mov_b64_e32 v[48:49], v[16:17]
	v_mov_b64_e32 v[32:33], v[16:17]
	v_lshl_add_u64 v[168:169], s[42:43], 0, v[166:167]
	s_mov_b64 s[12:13], s[42:43]
	s_mov_b64 s[14:15], s[40:41]
	v_add_u32_e32 v238, 0x4000, v166
	s_bitset1_b32 s90, 7
	v_mov_b32_e32 v0, 0
	s_mov_b32 s4, -1
	v_mov_b64_e32 v[62:63], v[14:15]
	v_mov_b64_e32 v[60:61], v[12:13]
	v_mov_b64_e32 v[58:59], v[10:11]
	v_mov_b64_e32 v[56:57], v[8:9]
	v_mov_b64_e32 v[54:55], v[6:7]
	v_mov_b64_e32 v[52:53], v[4:5]
	v_mov_b64_e32 v[50:51], v[2:3]
	v_mov_b64_e32 v[46:47], v[14:15]
	v_mov_b64_e32 v[44:45], v[12:13]
	v_mov_b64_e32 v[42:43], v[10:11]
	v_mov_b64_e32 v[40:41], v[8:9]
	v_mov_b64_e32 v[38:39], v[6:7]
	v_mov_b64_e32 v[36:37], v[4:5]
	v_mov_b64_e32 v[34:35], v[2:3]
	v_mov_b64_e32 v[30:31], v[14:15]
	v_mov_b64_e32 v[28:29], v[12:13]
	v_mov_b64_e32 v[26:27], v[10:11]
	v_mov_b64_e32 v[24:25], v[8:9]
	v_mov_b64_e32 v[22:23], v[6:7]
	v_mov_b64_e32 v[20:21], v[4:5]
	v_mov_b64_e32 v[18:19], v[2:3]
	s_waitcnt lgkmcnt(0)
	s_barrier
; #define SBAR() __builtin_amdgcn_sched_barrier(0)
; #define SLOAD(i, t) do { const long rb_ = TROW(t); const char* vt_ = (const char*)Vh + rb_ * (LDK * 2); const char* kt_ = (const char*)Kh + rb_ * (LDK * 2); \
;     sr_[i].vs0 = *(const bf16x8*)(vt_ + lo0); sr_[i].vs1 = *(const bf16x8*)(vt_ + lo0 + 32 * LDK * 2); \
;     sr_[i].ks0 = *(const bf16x8*)(kt_ + lo0); sr_[i].ks1 = *(const bf16x8*)(kt_ + lo0 + 32 * LDK * 2); } while (0)
; __device__ __forceinline__ void finishSM(f32x16& p0, f32x16& p1, float alpha, float& l_reg, bf16x8& pa0, bf16x8& pa1, bf16x8& pa2, bf16x8& pa3) {
; #pragma unroll
;   for (int r = 0; r < 16; ++r) p1[r] = __builtin_amdgcn_exp2f(p1[r]);
;   float ps = 0;
; #pragma unroll
;   for (int r = 0; r < 16; ++r) ps += p0[r];
; #pragma unroll
;   for (int r = 0; r < 16; ++r) ps += p1[r];
;   { auto rr = __builtin_amdgcn_permlane32_swap(__float_as_uint(ps), __float_as_uint(ps), false, false);
;     ps = __uint_as_float(rr[0]) + __uint_as_float(rr[1]); }
;   l_reg = l_reg * alpha + ps;
;     ...
;   PK4(p0, 0, pa0); PK4(p0, 8, pa1); PK4(p1, 0, pa2); PK4(p1, 8, pa3);
;     ...
; }
; __device__ __forceinline__ void qkt(f32x16& p0, f32x16& p1, const bf16_t* Ks, const bf16x8* qr, int r32, int hi) {
;   p0 = f32x16{}; p1 = f32x16{};
; #pragma unroll
;   for (int d0 = 0; d0 < 8; ++d0) { int cb = (d0 * 16 + hi * 8) * 2;
;     bf16x8 b0 = *reinterpret_cast<const bf16x8*>((const char*)Ks + KSWZ(r32, cb));
;     bf16x8 b1 = *reinterpret_cast<const bf16x8*>((const char*)Ks + KSWZ(32 + r32, cb));
;     p0 = __builtin_amdgcn_mfma_f32_32x32x16_bf16(b0, qr[d0], p0, 0, 0, 0);
;     p1 = __builtin_amdgcn_mfma_f32_32x32x16_bf16(b1, qr[d0], p1, 0, 0, 0); }
; }
; template <bool META>
; __device__ __forceinline__ void attn_unit(const bf16_t* Q, bf16_t* Oo, const bf16_t* __restrict__ Kb, const bf16_t* __restrict__ Vb, int b, int kvh, int h, int qb, char* lds, const int tid, const float* qn, const float* RT) {
;     ...
;   for (int j = 1; j + 1 < NT; j += 2) {
;     const int bn = bc == 2 ? 0 : bc + 1, bp = bc == 0 ? 2 : bc - 1;
;     SBAR(); qkt(pB0, pB1, (bf16_t*)((char*)K_lds + bc * SHM_K), qr, r32, hi);
;     finishSM(pA0, pA1, alA, l_reg, pa0, pa1, pa2, pa3); SBAR();
;     SLOAD(SO, j + 1);
;     SBAR();
;     pv_d0(o, vb0 + bp * (int)SHM_V, pa0, pa1, pa2, pa3); partialSM(pB0, pB1, m_reg, mnB, alB);
.LBB0_260:
	s_mov_b32 s6, s28
	v_sub_co_u32_e64 v66, s[0:1], s6, 1
	s_and_b64 s[0:1], s[0:1], exec
	v_readfirstlane_b32 s0, v66
	s_cselect_b32 s28, 2, s0
	s_lshl_b32 s9, s6, 14
	s_add_i32 s0, s9, 0
	v_add_u32_e32 v195, s0, v182
	ds_read_b128 v[66:69], v195 offset:49152
	ds_read_b128 v[70:73], v195 offset:50176
	ds_read_b128 v[210:213], v195 offset:51200
	ds_read_b128 v[214:217], v195 offset:52224
	s_waitcnt lgkmcnt(3)
	v_mfma_f32_32x32x16_bf16 v[82:97], v[66:69], v[98:101], 0
	v_exp_f32_e32 v144, v144
	v_exp_f32_e32 v145, v145
	v_exp_f32_e32 v142, v142
	v_exp_f32_e32 v143, v143
	v_exp_f32_e32 v140, v140
	v_exp_f32_e32 v141, v141
	v_exp_f32_e32 v138, v138
	s_waitcnt lgkmcnt(2)
	v_mfma_f32_32x32x16_bf16 v[66:81], v[70:73], v[98:101], 0
	v_exp_f32_e32 v139, v139
	v_exp_f32_e32 v136, v136
	v_exp_f32_e32 v137, v137
	v_exp_f32_e32 v134, v134
	v_exp_f32_e32 v135, v135
	v_exp_f32_e32 v132, v132
	v_exp_f32_e32 v133, v133
	s_waitcnt lgkmcnt(1)
	v_mfma_f32_32x32x16_bf16 v[82:97], v[210:213], v[102:105], v[82:97]
	v_exp_f32_e32 v130, v130
	v_exp_f32_e32 v131, v131
	s_waitcnt lgkmcnt(0)
	v_mfma_f32_32x32x16_bf16 v[66:81], v[214:217], v[102:105], v[66:81]
	ds_read_b128 v[210:213], v195 offset:53248
	ds_read_b128 v[214:217], v195 offset:54272
	s_waitcnt lgkmcnt(1)
	v_mfma_f32_32x32x16_bf16 v[82:97], v[210:213], v[106:109], v[82:97]
	s_waitcnt lgkmcnt(0)
	v_mfma_f32_32x32x16_bf16 v[66:81], v[214:217], v[106:109], v[66:81]
	ds_read_b128 v[210:213], v195 offset:55296
	ds_read_b128 v[214:217], v195 offset:56320
	s_waitcnt lgkmcnt(1)
	v_mfma_f32_32x32x16_bf16 v[82:97], v[210:213], v[110:113], v[82:97]
	s_waitcnt lgkmcnt(0)
	v_mfma_f32_32x32x16_bf16 v[66:81], v[214:217], v[110:113], v[66:81]
	ds_read_b128 v[210:213], v195 offset:57344
	ds_read_b128 v[214:217], v195 offset:58368
	s_waitcnt lgkmcnt(1)
	v_mfma_f32_32x32x16_bf16 v[82:97], v[210:213], v[114:117], v[82:97]
	s_waitcnt lgkmcnt(0)
	v_mfma_f32_32x32x16_bf16 v[66:81], v[214:217], v[114:117], v[66:81]
	ds_read_b128 v[210:213], v195 offset:59392
	ds_read_b128 v[214:217], v195 offset:60416
	s_waitcnt lgkmcnt(1)
	v_mfma_f32_32x32x16_bf16 v[82:97], v[210:213], v[118:121], v[82:97]
	s_waitcnt lgkmcnt(0)
	v_mfma_f32_32x32x16_bf16 v[66:81], v[214:217], v[118:121], v[66:81]
	ds_read_b128 v[210:213], v195 offset:61440
	ds_read_b128 v[214:217], v195 offset:62464
	s_waitcnt lgkmcnt(1)
	v_mfma_f32_32x32x16_bf16 v[82:97], v[210:213], v[122:125], v[82:97]
	s_waitcnt lgkmcnt(0)
	v_mfma_f32_32x32x16_bf16 v[66:81], v[214:217], v[122:125], v[66:81]
	ds_read_b128 v[210:213], v195 offset:63488
	ds_read_b128 v[214:217], v195 offset:64512
	v_add_f32_e32 v193, v147, v146
	v_add_f32_e32 v193, v148, v193
	v_add_f32_e32 v193, v159, v193
	v_add_f32_e32 v193, v160, v193
	v_add_f32_e32 v193, v209, v193
	v_add_f32_e32 v193, v149, v193
	v_add_f32_e32 v193, v161, v193
	v_add_f32_e32 v193, v151, v193
	v_add_f32_e32 v193, v153, v193
	v_add_f32_e32 v193, v154, v193
	v_add_f32_e32 v193, v157, v193
	v_add_f32_e32 v193, v152, v193
	v_add_f32_e32 v193, v155, v193
	v_add_f32_e32 v193, v156, v193
	v_add_f32_e32 v193, v158, v193
	v_add_f32_e32 v193, v144, v193
	v_add_f32_e32 v193, v145, v193
	v_add_f32_e32 v193, v142, v193
	v_add_f32_e32 v193, v143, v193
	v_add_f32_e32 v193, v140, v193
	v_add_f32_e32 v193, v141, v193
	v_add_f32_e32 v193, v138, v193
	v_add_f32_e32 v193, v139, v193
	v_add_f32_e32 v193, v136, v193
	v_add_f32_e32 v193, v137, v193
	s_waitcnt lgkmcnt(1)
	v_mfma_f32_32x32x16_bf16 v[82:97], v[210:213], v[126:129], v[82:97]
	v_add_f32_e32 v193, v134, v193
	v_add_f32_e32 v193, v135, v193
	v_add_f32_e32 v193, v132, v193
	v_add_f32_e32 v193, v133, v193
	v_add_f32_e32 v193, v130, v193
	v_add_f32_e32 v193, v131, v193
	v_mov_b32_e32 v195, v193
	s_waitcnt lgkmcnt(0)
	v_mfma_f32_32x32x16_bf16 v[66:81], v[214:217], v[126:129], v[66:81]
	v_cvt_pk_bf16_f32 v146, v146, v147
	v_cvt_pk_bf16_f32 v147, v148, v159
	v_cvt_pk_bf16_f32 v148, v160, v209
	v_permlane32_swap_b32_e32 v193, v195
	v_cvt_pk_bf16_f32 v149, v149, v161
	v_permlane32_swap_b32_e32 v146, v148
	v_cvt_pk_bf16_f32 v210, v151, v153
	v_cvt_pk_bf16_f32 v211, v154, v157
	v_cvt_pk_bf16_f32 v212, v152, v155
	v_cvt_pk_bf16_f32 v213, v156, v158
	v_cvt_pk_bf16_f32 v152, v144, v145
	v_cvt_pk_bf16_f32 v153, v142, v143
	v_cvt_pk_bf16_f32 v154, v140, v141
	v_cvt_pk_bf16_f32 v155, v138, v139
	v_cvt_pk_bf16_f32 v156, v136, v137
	v_cvt_pk_bf16_f32 v157, v134, v135
	v_cvt_pk_bf16_f32 v158, v132, v133
	v_cvt_pk_bf16_f32 v159, v130, v131
	v_permlane32_swap_b32_e32 v147, v149
	v_permlane32_swap_b32_e32 v210, v212
	v_permlane32_swap_b32_e32 v211, v213
	v_permlane32_swap_b32_e32 v152, v154
	v_permlane32_swap_b32_e32 v153, v155
	v_permlane32_swap_b32_e32 v156, v158
	v_permlane32_swap_b32_e32 v157, v159
	s_cmpk_lg_i32 s4, 0xfd
	s_cselect_b64 s[0:1], -1, 0
	s_cmpk_eq_i32 s4, 0xfd
	s_cselect_b64 s[40:41], -1, 0
	s_and_b64 s[10:11], s[40:41], exec
	s_cselect_b32 s11, s44, s91
	s_cselect_b32 s10, s31, s90
	s_lshl_b64 s[10:11], s[10:11], 9
	s_add_u32 s16, s12, s10
	s_addc_u32 s17, s13, s11
	s_add_u32 s18, s14, s10
	s_addc_u32 s19, s15, s11
	global_load_dwordx4 v[130:133], v166, s[16:17]
	global_load_dwordx4 v[134:137], v238, s[16:17]
	global_load_dwordx4 v[138:141], v184, s[18:19]
	global_load_dwordx4 v[142:145], v186, s[18:19]
	s_lshl_b32 s8, s28, 14
	v_add_u32_e32 v151, s8, v178
	ds_read_b64_tr_b16 v[214:215], v151 offset:0
	ds_read_b64_tr_b16 v[216:217], v151 offset:0x800
	ds_read_b64_tr_b16 v[218:219], v151 offset:0x1000
	ds_read_b64_tr_b16 v[220:221], v151 offset:0x1800
	ds_read_b64_tr_b16 v[222:223], v151 offset:0x2000
	ds_read_b64_tr_b16 v[224:225], v151 offset:0x2800
	ds_read_b64_tr_b16 v[226:227], v151 offset:0x3000
	ds_read_b64_tr_b16 v[228:229], v151 offset:0x3800
	s_waitcnt lgkmcnt(6)
; #define SBAR() __builtin_amdgcn_sched_barrier(0)
; __device__ __forceinline__ void partialSM(f32x16& p0, f32x16& p1, float& m_reg, float& mn, float& alpha) {
;   constexpr float C = ASCALE * 1.4426950408889634f;
;   float pmax = p0[0];
; #pragma unroll
;   for (int r = 1; r < 16; ++r) pmax = fmaxf(pmax, p0[r]);
; #pragma unroll
;   for (int r = 0; r < 16; ++r) pmax = fmaxf(pmax, p1[r]);
;   { auto rr = __builtin_amdgcn_permlane32_swap(__float_as_uint(pmax), __float_as_uint(pmax), false, false);
;     pmax = fmaxf(__uint_as_float(rr[0]), __uint_as_float(rr[1])); }
;   if (__builtin_expect(__all(pmax - m_reg <= ATHR / ASCALE), 1)) { mn = m_reg; alpha = 1.f; }
;   else { mn = fmaxf(m_reg, pmax); alpha = __builtin_amdgcn_exp2f((m_reg - mn) * C); m_reg = mn; }
; template <int D0> __device__ __forceinline__ void pv_one(f32x16& od, int vb, bf16x8 pa0, bf16x8 pa1, bf16x8 pa2, bf16x8 pa3) {
;   const s16x4 l0 = tr_read<v_rd_off(D0, 0, 0)>(vb), h0 = tr_read<v_rd_off(D0, 0, 1)>(vb), l1 = tr_read<v_rd_off(D0, 1, 0)>(vb), h1 = tr_read<v_rd_off(D0, 1, 1)>(vb);
;   const s16x4 l2 = tr_read<v_rd_off(D0, 2, 0)>(vb), h2 = tr_read<v_rd_off(D0, 2, 1)>(vb), l3 = tr_read<v_rd_off(D0, 3, 0)>(vb), h3 = tr_read<v_rd_off(D0, 3, 1)>(vb);
;   asm volatile("s_waitcnt lgkmcnt(0)" ::: "memory"); SBAR();
;     ...
;   od = __builtin_amdgcn_mfma_f32_32x32x16_bf16(pa0, PK(l0, h0), od, 0, 0, 0);
;   od = __builtin_amdgcn_mfma_f32_32x32x16_bf16(pa1, PK(l1, h1), od, 0, 0, 0);
;   od = __builtin_amdgcn_mfma_f32_32x32x16_bf16(pa2, PK(l2, h2), od, 0, 0, 0);
;   od = __builtin_amdgcn_mfma_f32_32x32x16_bf16(pa3, PK(l3, h3), od, 0, 0, 0);
;     ...
; }
; __device__ __forceinline__ void pv_d0(f32x16* o, int vb, bf16x8 pa0, bf16x8 pa1, bf16x8 pa2, bf16x8 pa3) {
;   pv_one<0>(o[0], vb, pa0, pa1, pa2, pa3); pv_one<1>(o[1], vb, pa0, pa1, pa2, pa3); pv_one<2>(o[2], vb, pa0, pa1, pa2, pa3); pv_one<3>(o[3], vb, pa0, pa1, pa2, pa3);
; }
	s_nop 0
	v_mfma_f32_32x32x16_bf16 v[2:17], v[146:149], v[214:217], v[2:17]
	ds_read_b64_tr_b16 v[214:215], v151 offset:0x200
	ds_read_b64_tr_b16 v[216:217], v151 offset:0xa00
	s_waitcnt lgkmcnt(6)
	v_mfma_f32_32x32x16_bf16 v[2:17], v[210:213], v[218:221], v[2:17]
	ds_read_b64_tr_b16 v[218:219], v151 offset:0x1200
	ds_read_b64_tr_b16 v[220:221], v151 offset:0x1a00
	s_waitcnt lgkmcnt(6)
	v_mfma_f32_32x32x16_bf16 v[2:17], v[152:155], v[222:225], v[2:17]
	ds_read_b64_tr_b16 v[222:223], v151 offset:0x2200
	ds_read_b64_tr_b16 v[224:225], v151 offset:0x2a00
	s_waitcnt lgkmcnt(6)
	v_mfma_f32_32x32x16_bf16 v[2:17], v[156:159], v[226:229], v[2:17]
	ds_read_b64_tr_b16 v[226:227], v151 offset:0x3200
	ds_read_b64_tr_b16 v[228:229], v151 offset:0x3a00
	s_waitcnt lgkmcnt(6)
	v_mfma_f32_32x32x16_bf16 v[50:65], v[146:149], v[214:217], v[50:65]
	ds_read_b64_tr_b16 v[214:215], v151 offset:0x400
	ds_read_b64_tr_b16 v[216:217], v151 offset:0xc00
	s_waitcnt lgkmcnt(6)
	v_mfma_f32_32x32x16_bf16 v[50:65], v[210:213], v[218:221], v[50:65]
	ds_read_b64_tr_b16 v[218:219], v151 offset:0x1400
	ds_read_b64_tr_b16 v[220:221], v151 offset:0x1c00
	s_waitcnt lgkmcnt(6)
	v_mfma_f32_32x32x16_bf16 v[50:65], v[152:155], v[222:225], v[50:65]
	ds_read_b64_tr_b16 v[222:223], v151 offset:0x2400
	ds_read_b64_tr_b16 v[224:225], v151 offset:0x2c00
	s_waitcnt lgkmcnt(6)
	v_mfma_f32_32x32x16_bf16 v[50:65], v[156:159], v[226:229], v[50:65]
	ds_read_b64_tr_b16 v[226:227], v151 offset:0x3400
	ds_read_b64_tr_b16 v[228:229], v151 offset:0x3c00
	s_waitcnt lgkmcnt(6)
	v_mfma_f32_32x32x16_bf16 v[34:49], v[146:149], v[214:217], v[34:49]
	ds_read_b64_tr_b16 v[214:215], v151 offset:0x600
	ds_read_b64_tr_b16 v[216:217], v151 offset:0xe00
	s_waitcnt lgkmcnt(6)
	v_mfma_f32_32x32x16_bf16 v[34:49], v[210:213], v[218:221], v[34:49]
	ds_read_b64_tr_b16 v[218:219], v151 offset:0x1600
	ds_read_b64_tr_b16 v[220:221], v151 offset:0x1e00
	s_waitcnt lgkmcnt(6)
	v_mfma_f32_32x32x16_bf16 v[34:49], v[152:155], v[222:225], v[34:49]
	ds_read_b64_tr_b16 v[222:223], v151 offset:0x2600
	ds_read_b64_tr_b16 v[224:225], v151 offset:0x2e00
	s_waitcnt lgkmcnt(6)
	v_mfma_f32_32x32x16_bf16 v[34:49], v[156:159], v[226:229], v[34:49]
	ds_read_b64_tr_b16 v[226:227], v151 offset:0x3600
	ds_read_b64_tr_b16 v[228:229], v151 offset:0x3e00
	s_waitcnt lgkmcnt(6)
	v_mfma_f32_32x32x16_bf16 v[18:33], v[146:149], v[214:217], v[18:33]
	v_max_f32_e32 v146, v82, v83
	v_max3_f32 v146, v146, v84, v85
	v_max3_f32 v146, v146, v86, v87
	v_max3_f32 v146, v146, v88, v89
	v_max3_f32 v146, v146, v90, v91
	v_max3_f32 v146, v146, v92, v93
	v_max3_f32 v146, v146, v94, v95
	v_max3_f32 v146, v146, v96, v97
	v_max3_f32 v146, v146, v66, v67
	s_waitcnt lgkmcnt(4)
	v_mfma_f32_32x32x16_bf16 v[18:33], v[210:213], v[218:221], v[18:33]
	v_max3_f32 v146, v146, v68, v69
	v_max3_f32 v146, v146, v70, v71
	v_max3_f32 v146, v146, v72, v73
	v_max3_f32 v146, v146, v74, v75
	v_max3_f32 v146, v146, v76, v77
	v_max3_f32 v146, v146, v78, v79
	v_max3_f32 v146, v146, v80, v81
	v_mov_b32_e32 v147, v146
	s_waitcnt lgkmcnt(2)
	v_mfma_f32_32x32x16_bf16 v[18:33], v[152:155], v[222:225], v[18:33]
	s_nop 0
	v_permlane32_swap_b32_e32 v146, v147
	v_max_f32_e32 v146, v146, v147
	v_sub_f32_e32 v147, v146, v150
	v_cmp_ge_f32_e32 vcc, s25, v147
	v_max_f32_e32 v146, v150, v146
	v_sub_f32_e32 v147, v150, v146
	s_cmp_eq_u64 vcc, exec
	v_mul_f32_e32 v147, 0x3e0293ee, v147
	s_waitcnt lgkmcnt(0)
	v_mfma_f32_32x32x16_bf16 v[18:33], v[156:159], v[226:229], v[18:33]
	s_cselect_b64 s[42:43], -1, 0
	v_exp_f32_e32 v147, v147
	s_add_i32 s7, s9, 0x4000
	s_cmp_lg_u32 s6, 2
	s_cselect_b32 s6, s7, 0
	s_add_i32 s10, s6, 0
	v_cndmask_b32_e64 v196, v147, 1.0, s[42:43]
	v_add_u32_e32 v147, s10, v176
	s_waitcnt vmcnt(0)
	s_waitcnt vmcnt(3)
	ds_write_b128 v147, v[130:133]
	s_waitcnt vmcnt(2)
	ds_write_b128 v147, v[134:137] offset:8192
	v_add_u32_e32 v147, s10, v179
	s_waitcnt vmcnt(1)
	ds_write_b128 v147, v[138:141] offset:49152
	v_cmp_gt_f32_e32 vcc, 1.0, v196
	s_waitcnt vmcnt(0)
	ds_write_b128 v147, v[142:145] offset:50176
	s_cbranch_vccz .LBB0_264
	s_and_saveexec_b64 s[6:7], s[38:39]
	ds_write_b32 v190, v196 offset:128
	s_or_b64 exec, exec, s[6:7]
	s_waitcnt lgkmcnt(0)
	v_add_u32_e32 v147, v173, v181
	ds_read_b128 v[152:155], v147 offset:224
	ds_read_b128 v[156:159], v147 offset:192
	ds_read_b128 v[210:213], v147 offset:160
	ds_read_b128 v[214:217], v147 offset:128
	s_waitcnt lgkmcnt(3)
	v_pk_mul_f32 v[14:15], v[14:15], v[152:153]
	s_waitcnt lgkmcnt(2)
	v_pk_mul_f32 v[10:11], v[10:11], v[156:157]
	s_waitcnt lgkmcnt(1)
	v_pk_mul_f32 v[6:7], v[6:7], v[210:211]
	v_pk_mul_f32 v[16:17], v[16:17], v[154:155]
	v_pk_mul_f32 v[12:13], v[12:13], v[158:159]
	v_pk_mul_f32 v[8:9], v[8:9], v[212:213]
	s_waitcnt lgkmcnt(0)
	v_pk_mul_f32 v[4:5], v[4:5], v[216:217]
	v_pk_mul_f32 v[2:3], v[2:3], v[214:215]
	v_pk_mul_f32 v[62:63], v[62:63], v[152:153]
	v_pk_mul_f32 v[58:59], v[58:59], v[156:157]
	v_pk_mul_f32 v[54:55], v[54:55], v[210:211]
	v_pk_mul_f32 v[64:65], v[64:65], v[154:155]
	v_pk_mul_f32 v[60:61], v[60:61], v[158:159]
	v_pk_mul_f32 v[56:57], v[56:57], v[212:213]
	v_pk_mul_f32 v[52:53], v[52:53], v[216:217]
	v_pk_mul_f32 v[50:51], v[50:51], v[214:215]
	v_pk_mul_f32 v[46:47], v[46:47], v[152:153]
	v_pk_mul_f32 v[42:43], v[42:43], v[156:157]
	v_pk_mul_f32 v[38:39], v[38:39], v[210:211]
	v_pk_mul_f32 v[48:49], v[48:49], v[154:155]
	v_pk_mul_f32 v[44:45], v[44:45], v[158:159]
	v_pk_mul_f32 v[40:41], v[40:41], v[212:213]
	v_pk_mul_f32 v[36:37], v[36:37], v[216:217]
	v_pk_mul_f32 v[34:35], v[34:35], v[214:215]
	v_pk_mul_f32 v[30:31], v[30:31], v[152:153]
	v_pk_mul_f32 v[26:27], v[26:27], v[156:157]
	v_pk_mul_f32 v[22:23], v[22:23], v[210:211]
	v_pk_mul_f32 v[32:33], v[32:33], v[154:155]
	v_pk_mul_f32 v[28:29], v[28:29], v[158:159]
	v_pk_mul_f32 v[24:25], v[24:25], v[212:213]
	v_pk_mul_f32 v[20:21], v[20:21], v[216:217]
	v_pk_mul_f32 v[18:19], v[18:19], v[214:215]
; #define SBAR() __builtin_amdgcn_sched_barrier(0)
; __device__ __forceinline__ void partialSM(f32x16& p0, f32x16& p1, float& m_reg, float& mn, float& alpha) {
;     ...
;   float mnC = -mn * C;
; #pragma unroll
;   for (int r = 0; r < 16; ++r) p0[r] = fmaf(p0[r], C, mnC);
; #pragma unroll
;   for (int r = 0; r < 16; ++r) p1[r] = fmaf(p1[r], C, mnC);
; #pragma unroll
;   for (int r = 0; r < 16; ++r) p0[r] = __builtin_amdgcn_exp2f(p0[r]);
; }
; __device__ __forceinline__ void finishSM(f32x16& p0, f32x16& p1, float alpha, float& l_reg, bf16x8& pa0, bf16x8& pa1, bf16x8& pa2, bf16x8& pa3) {
; #pragma unroll
;   for (int r = 0; r < 16; ++r) p1[r] = __builtin_amdgcn_exp2f(p1[r]);
;   float ps = 0;
; #pragma unroll
;   for (int r = 0; r < 16; ++r) ps += p0[r];
; #pragma unroll
;   for (int r = 0; r < 16; ++r) ps += p1[r];
;   { auto rr = __builtin_amdgcn_permlane32_swap(__float_as_uint(ps), __float_as_uint(ps), false, false);
;     ps = __uint_as_float(rr[0]) + __uint_as_float(rr[1]); }
;   l_reg = l_reg * alpha + ps;
;     ...
;   PK4(p0, 0, pa0); PK4(p0, 8, pa1); PK4(p1, 0, pa2); PK4(p1, 8, pa3);
;     ...
; }
; __device__ __forceinline__ void qkt(f32x16& p0, f32x16& p1, const bf16_t* Ks, const bf16x8* qr, int r32, int hi) {
;   p0 = f32x16{}; p1 = f32x16{};
; #pragma unroll
;   for (int d0 = 0; d0 < 8; ++d0) { int cb = (d0 * 16 + hi * 8) * 2;
;     bf16x8 b0 = *reinterpret_cast<const bf16x8*>((const char*)Ks + KSWZ(r32, cb));
;     bf16x8 b1 = *reinterpret_cast<const bf16x8*>((const char*)Ks + KSWZ(32 + r32, cb));
;     p0 = __builtin_amdgcn_mfma_f32_32x32x16_bf16(b0, qr[d0], p0, 0, 0, 0);
;     p1 = __builtin_amdgcn_mfma_f32_32x32x16_bf16(b1, qr[d0], p1, 0, 0, 0); }
; }
; template <bool META>
; __device__ __forceinline__ void attn_unit(const bf16_t* Q, bf16_t* Oo, const bf16_t* __restrict__ Kb, const bf16_t* __restrict__ Vb, int b, int kvh, int h, int qb, char* lds, const int tid, const float* qn, const float* RT) {
;     ...
;     SBAR(); qkt(pA0, pA1, (bf16_t*)((char*)K_lds + bn * SHM_K), qr, r32, hi);
;     if (j + 1 == NT - 1) mask_last(pA0, pA1);
;     finishSM(pB0, pB1, alB, l_reg, pa0, pa1, pa2, pa3); SBAR();
;     if (j + 2 < NT) SLOAD(SE, j + 2);
.LBB0_264:
	v_cndmask_b32_e64 v209, v146, v150, s[42:43]
	v_mul_f32_e32 v154, 0xbe0293ee, v209
	s_add_i32 s4, s4, 2
	v_fmamk_f32 v82, v82, 0x3e0293ee, v154
	v_fmamk_f32 v83, v83, 0x3e0293ee, v154
	v_fmamk_f32 v84, v84, 0x3e0293ee, v154
	v_fmamk_f32 v85, v85, 0x3e0293ee, v154
	v_fmamk_f32 v86, v86, 0x3e0293ee, v154
	v_fmamk_f32 v87, v87, 0x3e0293ee, v154
	v_fmamk_f32 v88, v88, 0x3e0293ee, v154
	v_fmamk_f32 v89, v89, 0x3e0293ee, v154
	v_fmamk_f32 v90, v90, 0x3e0293ee, v154
	v_fmamk_f32 v91, v91, 0x3e0293ee, v154
	v_fmamk_f32 v92, v92, 0x3e0293ee, v154
	v_fmamk_f32 v93, v93, 0x3e0293ee, v154
	v_fmamk_f32 v94, v94, 0x3e0293ee, v154
	v_fmamk_f32 v95, v95, 0x3e0293ee, v154
	v_fmamk_f32 v96, v96, 0x3e0293ee, v154
	v_fmamk_f32 v97, v97, 0x3e0293ee, v154
	v_fmamk_f32 v155, v66, 0x3e0293ee, v154
	v_fmamk_f32 v156, v67, 0x3e0293ee, v154
	v_fmamk_f32 v157, v68, 0x3e0293ee, v154
	v_fmamk_f32 v158, v69, 0x3e0293ee, v154
	v_fmamk_f32 v159, v70, 0x3e0293ee, v154
	v_fmamk_f32 v160, v71, 0x3e0293ee, v154
	v_fmamk_f32 v161, v72, 0x3e0293ee, v154
	v_fmamk_f32 v198, v73, 0x3e0293ee, v154
	v_fmamk_f32 v199, v74, 0x3e0293ee, v154
	v_fmamk_f32 v200, v75, 0x3e0293ee, v154
	v_fmamk_f32 v201, v76, 0x3e0293ee, v154
	v_fmamk_f32 v202, v77, 0x3e0293ee, v154
	v_fmamk_f32 v203, v78, 0x3e0293ee, v154
	v_fmamk_f32 v204, v79, 0x3e0293ee, v154
	v_fmamk_f32 v205, v80, 0x3e0293ee, v154
	v_fmac_f32_e32 v154, 0x3e0293ee, v81
	v_exp_f32_e32 v206, v82
	v_exp_f32_e32 v207, v83
	v_exp_f32_e32 v212, v84
	v_exp_f32_e32 v213, v85
	v_exp_f32_e32 v214, v86
	v_exp_f32_e32 v215, v87
	v_exp_f32_e32 v216, v88
	v_exp_f32_e32 v217, v89
	v_exp_f32_e32 v218, v90
	v_exp_f32_e32 v219, v91
	v_exp_f32_e32 v220, v92
	v_exp_f32_e32 v221, v93
	v_exp_f32_e32 v222, v94
	v_exp_f32_e32 v223, v95
	v_exp_f32_e32 v224, v96
	v_exp_f32_e32 v225, v97
	s_waitcnt lgkmcnt(0)
	s_barrier
	v_add_u32_e32 v211, s10, v182
	ds_read_b128 v[66:69], v211 offset:49152
	ds_read_b128 v[82:85], v211 offset:50176
	ds_read_b128 v[146:149], v211 offset:51200
	ds_read_b128 v[150:153], v211 offset:52224
	v_exp_f32_e32 v155, v155
	s_waitcnt lgkmcnt(3)
	v_mfma_f32_32x32x16_bf16 v[66:81], v[66:69], v[98:101], 0
	v_exp_f32_e32 v156, v156
	v_exp_f32_e32 v157, v157
	v_exp_f32_e32 v158, v158
	v_exp_f32_e32 v159, v159
	v_exp_f32_e32 v160, v160
	v_exp_f32_e32 v161, v161
	v_exp_f32_e32 v198, v198
	s_waitcnt lgkmcnt(2)
	v_mfma_f32_32x32x16_bf16 v[82:97], v[82:85], v[98:101], 0
	v_exp_f32_e32 v199, v199
	v_exp_f32_e32 v200, v200
	v_exp_f32_e32 v201, v201
	v_exp_f32_e32 v202, v202
	v_exp_f32_e32 v203, v203
	v_exp_f32_e32 v204, v204
	v_exp_f32_e32 v205, v205
	s_waitcnt lgkmcnt(1)
	v_mfma_f32_32x32x16_bf16 v[66:81], v[146:149], v[102:105], v[66:81]
	v_exp_f32_e32 v226, v154
	v_cvt_pk_bf16_f32 v154, v155, v156
	s_waitcnt lgkmcnt(0)
	v_mfma_f32_32x32x16_bf16 v[82:97], v[150:153], v[102:105], v[82:97]
	ds_read_b128 v[146:149], v211 offset:53248
	ds_read_b128 v[150:153], v211 offset:54272
	s_waitcnt lgkmcnt(1)
	v_mfma_f32_32x32x16_bf16 v[66:81], v[146:149], v[106:109], v[66:81]
	s_waitcnt lgkmcnt(0)
	v_mfma_f32_32x32x16_bf16 v[82:97], v[150:153], v[106:109], v[82:97]
	ds_read_b128 v[146:149], v211 offset:55296
	ds_read_b128 v[150:153], v211 offset:56320
	s_waitcnt lgkmcnt(1)
	v_mfma_f32_32x32x16_bf16 v[66:81], v[146:149], v[110:113], v[66:81]
	s_waitcnt lgkmcnt(0)
	v_mfma_f32_32x32x16_bf16 v[82:97], v[150:153], v[110:113], v[82:97]
	ds_read_b128 v[146:149], v211 offset:57344
	ds_read_b128 v[150:153], v211 offset:58368
	s_waitcnt lgkmcnt(1)
	v_mfma_f32_32x32x16_bf16 v[66:81], v[146:149], v[114:117], v[66:81]
	s_waitcnt lgkmcnt(0)
	v_mfma_f32_32x32x16_bf16 v[82:97], v[150:153], v[114:117], v[82:97]
	ds_read_b128 v[146:149], v211 offset:59392
	ds_read_b128 v[150:153], v211 offset:60416
	s_waitcnt lgkmcnt(1)
	v_mfma_f32_32x32x16_bf16 v[66:81], v[146:149], v[118:121], v[66:81]
	s_waitcnt lgkmcnt(0)
	v_mfma_f32_32x32x16_bf16 v[82:97], v[150:153], v[118:121], v[82:97]
	ds_read_b128 v[146:149], v211 offset:61440
	ds_read_b128 v[150:153], v211 offset:62464
	s_waitcnt lgkmcnt(1)
	v_mfma_f32_32x32x16_bf16 v[66:81], v[146:149], v[122:125], v[66:81]
	s_waitcnt lgkmcnt(0)
	v_mfma_f32_32x32x16_bf16 v[82:97], v[150:153], v[122:125], v[82:97]
	ds_read_b128 v[146:149], v211 offset:63488
	ds_read_b128 v[150:153], v211 offset:64512
	s_waitcnt lgkmcnt(1)
	v_mfma_f32_32x32x16_bf16 v[66:81], v[146:149], v[126:129], v[66:81]
	v_add_f32_e32 v146, v207, v206
	v_add_f32_e32 v146, v212, v146
	v_add_f32_e32 v146, v213, v146
	v_add_f32_e32 v146, v214, v146
	v_add_f32_e32 v146, v215, v146
	v_add_f32_e32 v146, v216, v146
	v_add_f32_e32 v146, v217, v146
	v_add_f32_e32 v146, v218, v146
	v_add_f32_e32 v146, v219, v146
	v_add_f32_e32 v146, v220, v146
	v_add_f32_e32 v146, v221, v146
	v_add_f32_e32 v146, v222, v146
	v_add_f32_e32 v146, v223, v146
	v_add_f32_e32 v146, v224, v146
	v_add_f32_e32 v146, v225, v146
	v_add_f32_e32 v146, v155, v146
	v_add_f32_e32 v146, v156, v146
	v_add_f32_e32 v146, v157, v146
	v_add_f32_e32 v146, v158, v146
	v_add_f32_e32 v146, v159, v146
	v_add_f32_e32 v146, v160, v146
	v_add_f32_e32 v146, v161, v146
	v_add_f32_e32 v146, v198, v146
	v_add_f32_e32 v146, v199, v146
	v_add_f32_e32 v146, v200, v146
	s_waitcnt lgkmcnt(0)
	v_mfma_f32_32x32x16_bf16 v[82:97], v[150:153], v[126:129], v[82:97]
	v_add_f32_e32 v146, v201, v146
	v_add_f32_e32 v146, v202, v146
	v_add_f32_e32 v146, v203, v146
	v_add_f32_e32 v146, v204, v146
	v_add_f32_e32 v146, v205, v146
	v_add_f32_e32 v210, v226, v146
	v_mov_b32_e32 v211, v210
	v_cvt_pk_bf16_f32 v146, v206, v207
	v_cvt_pk_bf16_f32 v147, v212, v213
	v_cvt_pk_bf16_f32 v148, v214, v215
	v_cvt_pk_bf16_f32 v149, v216, v217
	v_cvt_pk_bf16_f32 v150, v218, v219
	v_cvt_pk_bf16_f32 v151, v220, v221
	v_cvt_pk_bf16_f32 v152, v222, v223
	v_cvt_pk_bf16_f32 v153, v224, v225
	v_cvt_pk_bf16_f32 v155, v157, v158
	v_cvt_pk_bf16_f32 v156, v159, v160
	v_cvt_pk_bf16_f32 v157, v161, v198
	v_cvt_pk_bf16_f32 v158, v199, v200
	v_cvt_pk_bf16_f32 v159, v201, v202
	v_cvt_pk_bf16_f32 v160, v203, v204
	v_cvt_pk_bf16_f32 v161, v205, v226
	v_permlane32_swap_b32_e32 v210, v211
	v_permlane32_swap_b32_e32 v146, v148
	v_permlane32_swap_b32_e32 v147, v149
	v_permlane32_swap_b32_e32 v150, v152
	v_permlane32_swap_b32_e32 v151, v153
	v_permlane32_swap_b32_e32 v154, v156
	v_permlane32_swap_b32_e32 v155, v157
	v_permlane32_swap_b32_e32 v158, v160
	v_permlane32_swap_b32_e32 v159, v161
	s_andn2_b64 vcc, exec, s[0:1]
	s_cbranch_vccnz .LBB0_266
	s_add_u32 s0, s90, 64
	s_addc_u32 s1, s91, 0
	s_cmpk_lt_u32 s4, 0xfe
	s_cselect_b32 s1, s1, s44
	s_cselect_b32 s0, s0, s31
	s_lshl_b64 s[0:1], s[0:1], 9
	s_add_u32 s16, s12, s0
	s_addc_u32 s17, s13, s1
	s_add_u32 s18, s14, s0
	s_addc_u32 s19, s15, s1
	global_load_dwordx4 v[130:133], v166, s[16:17]
	global_load_dwordx4 v[134:137], v238, s[16:17]
	global_load_dwordx4 v[138:141], v184, s[18:19]
	global_load_dwordx4 v[142:145], v186, s[18:19]

; #define SBAR() __builtin_amdgcn_sched_barrier(0)
; #define SWRITE(bb, i) do { *(bf16x8*)((char*)V_lds + (bb) * SHM_V + vst0) = sr_[i].vs0;          \
;     *(bf16x8*)((char*)V_lds + (bb) * SHM_V + vst1) = sr_[i].vs1; int kc = sc * 2;               \
;     *(bf16x8*)((char*)K_lds + (bb) * SHM_K + KSWZ(sr, kc)) = sr_[i].ks0;                       \
;     *(bf16x8*)((char*)K_lds + (bb) * SHM_K + KSWZ(32 + sr, kc)) = sr_[i].ks1; } while (0)
; #define SWAIT() asm volatile("s_waitcnt vmcnt(0)" ::: "memory")
; #define RESC(a) do { if (__any((a) < 1.f)) { if (hi == 0) al_l[r32] = (a); asm volatile("s_waitcnt lgkmcnt(0)" ::: "memory"); \
;     _Pragma("unroll") for (int d = 0; d < 4; ++d) _Pragma("unroll") for (int r = 0; r < 16; ++r) o[d][r] *= al_l[crow(r, hi)]; } } while (0)
; template <int D0> __device__ __forceinline__ void pv_one(f32x16& od, int vb, bf16x8 pa0, bf16x8 pa1, bf16x8 pa2, bf16x8 pa3) {
;   const s16x4 l0 = tr_read<v_rd_off(D0, 0, 0)>(vb), h0 = tr_read<v_rd_off(D0, 0, 1)>(vb), l1 = tr_read<v_rd_off(D0, 1, 0)>(vb), h1 = tr_read<v_rd_off(D0, 1, 1)>(vb);
;   const s16x4 l2 = tr_read<v_rd_off(D0, 2, 0)>(vb), h2 = tr_read<v_rd_off(D0, 2, 1)>(vb), l3 = tr_read<v_rd_off(D0, 3, 0)>(vb), h3 = tr_read<v_rd_off(D0, 3, 1)>(vb);
;   asm volatile("s_waitcnt lgkmcnt(0)" ::: "memory"); SBAR();
;     ...
;   od = __builtin_amdgcn_mfma_f32_32x32x16_bf16(pa0, PK(l0, h0), od, 0, 0, 0);
;   od = __builtin_amdgcn_mfma_f32_32x32x16_bf16(pa1, PK(l1, h1), od, 0, 0, 0);
;   od = __builtin_amdgcn_mfma_f32_32x32x16_bf16(pa2, PK(l2, h2), od, 0, 0, 0);
;   od = __builtin_amdgcn_mfma_f32_32x32x16_bf16(pa3, PK(l3, h3), od, 0, 0, 0);
;     ...
; }
; __device__ __forceinline__ void pv_d0(f32x16* o, int vb, bf16x8 pa0, bf16x8 pa1, bf16x8 pa2, bf16x8 pa3) {
;   pv_one<0>(o[0], vb, pa0, pa1, pa2, pa3); pv_one<1>(o[1], vb, pa0, pa1, pa2, pa3); pv_one<2>(o[2], vb, pa0, pa1, pa2, pa3); pv_one<3>(o[3], vb, pa0, pa1, pa2, pa3);
; }
; template <bool META>
; __device__ __forceinline__ void attn_unit(const bf16_t* Q, bf16_t* Oo, const bf16_t* __restrict__ Kb, const bf16_t* __restrict__ Vb, int b, int kvh, int h, int qb, char* lds, const int tid, const float* qn, const float* RT) {
;     ...
;     pv_d0(o, vb0 + bc * (int)SHM_V, pa0, pa1, pa2, pa3); partialSM(pA0, pA1, m_reg, mnA, alA);
;     SWAIT(); SWRITE(bp, SO);
;     RESC(alA); __syncthreads();
.Latt_nomask:
	v_add_u32_e32 v198, s9, v178
	ds_read_b64_tr_b16 v[212:213], v198 offset:0
	ds_read_b64_tr_b16 v[214:215], v198 offset:0x800
	ds_read_b64_tr_b16 v[216:217], v198 offset:0x1000
	ds_read_b64_tr_b16 v[218:219], v198 offset:0x1800
	ds_read_b64_tr_b16 v[220:221], v198 offset:0x2000
	ds_read_b64_tr_b16 v[222:223], v198 offset:0x2800
	ds_read_b64_tr_b16 v[224:225], v198 offset:0x3000
	ds_read_b64_tr_b16 v[226:227], v198 offset:0x3800
	s_waitcnt lgkmcnt(6)
	s_nop 0
	v_mfma_f32_32x32x16_bf16 v[2:17], v[146:149], v[212:215], v[2:17]
	ds_read_b64_tr_b16 v[212:213], v198 offset:0x200
	ds_read_b64_tr_b16 v[214:215], v198 offset:0xa00
	s_waitcnt lgkmcnt(6)
	v_mfma_f32_32x32x16_bf16 v[2:17], v[150:153], v[216:219], v[2:17]
	ds_read_b64_tr_b16 v[216:217], v198 offset:0x1200
	ds_read_b64_tr_b16 v[218:219], v198 offset:0x1a00
	s_waitcnt lgkmcnt(6)
	v_mfma_f32_32x32x16_bf16 v[2:17], v[154:157], v[220:223], v[2:17]
	ds_read_b64_tr_b16 v[220:221], v198 offset:0x2200
	ds_read_b64_tr_b16 v[222:223], v198 offset:0x2a00
	s_waitcnt lgkmcnt(6)
	v_mfma_f32_32x32x16_bf16 v[2:17], v[158:161], v[224:227], v[2:17]
	ds_read_b64_tr_b16 v[224:225], v198 offset:0x3200
	ds_read_b64_tr_b16 v[226:227], v198 offset:0x3a00
	s_waitcnt lgkmcnt(6)
	v_mfma_f32_32x32x16_bf16 v[50:65], v[146:149], v[212:215], v[50:65]
	ds_read_b64_tr_b16 v[212:213], v198 offset:0x400
	ds_read_b64_tr_b16 v[214:215], v198 offset:0xc00
	s_waitcnt lgkmcnt(6)
	v_mfma_f32_32x32x16_bf16 v[50:65], v[150:153], v[216:219], v[50:65]
	ds_read_b64_tr_b16 v[216:217], v198 offset:0x1400
	ds_read_b64_tr_b16 v[218:219], v198 offset:0x1c00
	s_waitcnt lgkmcnt(6)
	v_mfma_f32_32x32x16_bf16 v[50:65], v[154:157], v[220:223], v[50:65]
	ds_read_b64_tr_b16 v[220:221], v198 offset:0x2400
	ds_read_b64_tr_b16 v[222:223], v198 offset:0x2c00
	s_waitcnt lgkmcnt(6)
	v_mfma_f32_32x32x16_bf16 v[50:65], v[158:161], v[224:227], v[50:65]
	ds_read_b64_tr_b16 v[224:225], v198 offset:0x3400
	ds_read_b64_tr_b16 v[226:227], v198 offset:0x3c00
	s_waitcnt lgkmcnt(6)
	v_mfma_f32_32x32x16_bf16 v[34:49], v[146:149], v[212:215], v[34:49]
	ds_read_b64_tr_b16 v[212:213], v198 offset:0x600
	ds_read_b64_tr_b16 v[214:215], v198 offset:0xe00
	s_waitcnt lgkmcnt(6)
	v_mfma_f32_32x32x16_bf16 v[34:49], v[150:153], v[216:219], v[34:49]
	ds_read_b64_tr_b16 v[216:217], v198 offset:0x1600
	ds_read_b64_tr_b16 v[218:219], v198 offset:0x1e00
	s_waitcnt lgkmcnt(6)
	v_mfma_f32_32x32x16_bf16 v[34:49], v[154:157], v[220:223], v[34:49]
	ds_read_b64_tr_b16 v[220:221], v198 offset:0x2600
	ds_read_b64_tr_b16 v[222:223], v198 offset:0x2e00
	s_waitcnt lgkmcnt(6)
	v_mfma_f32_32x32x16_bf16 v[34:49], v[158:161], v[224:227], v[34:49]
	ds_read_b64_tr_b16 v[224:225], v198 offset:0x3600
	ds_read_b64_tr_b16 v[226:227], v198 offset:0x3e00
	s_waitcnt lgkmcnt(6)
	v_mfma_f32_32x32x16_bf16 v[18:33], v[146:149], v[212:215], v[18:33]
	v_max_f32_e32 v230, v66, v67
	v_max3_f32 v230, v230, v68, v69
	v_max3_f32 v230, v230, v70, v71
	v_max3_f32 v230, v230, v72, v73
	v_max3_f32 v230, v230, v74, v75
	v_max3_f32 v230, v230, v76, v77
	v_max3_f32 v230, v230, v78, v79
	s_waitcnt lgkmcnt(4)
	v_mfma_f32_32x32x16_bf16 v[18:33], v[150:153], v[216:219], v[18:33]
	v_max3_f32 v230, v230, v80, v81
	v_max3_f32 v230, v230, v82, v83
	v_max3_f32 v230, v230, v84, v85
	v_max3_f32 v230, v230, v86, v87
	v_max3_f32 v230, v230, v88, v89
	v_max3_f32 v230, v230, v90, v91
	v_max3_f32 v230, v230, v92, v93
	v_max3_f32 v230, v230, v94, v95
	s_waitcnt lgkmcnt(2)
	v_mfma_f32_32x32x16_bf16 v[18:33], v[154:157], v[220:223], v[18:33]
	v_max3_f32 v230, v230, v96, v97
	v_mov_b32_e32 v231, v230
	s_nop 1
	v_permlane32_swap_b32_e32 v230, v231
	v_max_f32_e32 v230, v230, v231
	v_sub_f32_e32 v231, v230, v209
	v_cmp_ge_f32_e32 vcc, s25, v231
	v_max_f32_e32 v231, v209, v230
	s_waitcnt lgkmcnt(0)
	v_mfma_f32_32x32x16_bf16 v[18:33], v[158:161], v[224:227], v[18:33]
	v_sub_f32_e32 v230, v209, v231
	v_mul_f32_e32 v230, 0x3e0293ee, v230
	s_cmp_eq_u64 vcc, exec
	v_exp_f32_e32 v230, v230
	s_cselect_b64 s[40:41], -1, 0
	s_add_i32 s0, s8, 0
	v_add_u32_e32 v232, s0, v176
	s_waitcnt vmcnt(0)
	s_waitcnt vmcnt(3)
	ds_write_b128 v232, v[130:133]
	v_cndmask_b32_e64 v230, v230, 1.0, s[40:41]
	s_waitcnt vmcnt(2)
	ds_write_b128 v232, v[134:137] offset:8192
	v_add_u32_e32 v232, s0, v179
	s_waitcnt vmcnt(1)
	ds_write_b128 v232, v[138:141] offset:49152
	v_cmp_gt_f32_e32 vcc, 1.0, v230
	s_waitcnt vmcnt(0)
	ds_write_b128 v232, v[142:145] offset:50176
	s_cbranch_vccz .LBB0_270
	s_and_saveexec_b64 s[0:1], s[38:39]
	ds_write_b32 v190, v230 offset:128
	s_or_b64 exec, exec, s[0:1]
	s_waitcnt lgkmcnt(0)
	v_add_u32_e32 v236, v173, v181
	ds_read_b128 v[232:235], v236 offset:224
	ds_read_b128 v[130:133], v236 offset:192
	ds_read_b128 v[134:137], v236 offset:160
	ds_read_b128 v[138:141], v236 offset:128
	s_waitcnt lgkmcnt(3)
	v_pk_mul_f32 v[14:15], v[14:15], v[232:233]
	s_waitcnt lgkmcnt(2)
	v_pk_mul_f32 v[10:11], v[10:11], v[130:131]
	s_waitcnt lgkmcnt(1)
	v_pk_mul_f32 v[6:7], v[6:7], v[134:135]
	v_pk_mul_f32 v[16:17], v[16:17], v[234:235]
	v_pk_mul_f32 v[12:13], v[12:13], v[132:133]
	v_pk_mul_f32 v[8:9], v[8:9], v[136:137]
	s_waitcnt lgkmcnt(0)
	v_pk_mul_f32 v[4:5], v[4:5], v[140:141]
	v_pk_mul_f32 v[2:3], v[2:3], v[138:139]
	v_pk_mul_f32 v[62:63], v[62:63], v[232:233]
	v_pk_mul_f32 v[58:59], v[58:59], v[130:131]
	v_pk_mul_f32 v[54:55], v[54:55], v[134:135]
	v_pk_mul_f32 v[64:65], v[64:65], v[234:235]
	v_pk_mul_f32 v[60:61], v[60:61], v[132:133]
	v_pk_mul_f32 v[56:57], v[56:57], v[136:137]
	v_pk_mul_f32 v[52:53], v[52:53], v[140:141]
	v_pk_mul_f32 v[50:51], v[50:51], v[138:139]
	v_pk_mul_f32 v[46:47], v[46:47], v[232:233]
	v_pk_mul_f32 v[42:43], v[42:43], v[130:131]
	v_pk_mul_f32 v[38:39], v[38:39], v[134:135]
	v_pk_mul_f32 v[48:49], v[48:49], v[234:235]
	v_pk_mul_f32 v[44:45], v[44:45], v[132:133]
	v_pk_mul_f32 v[40:41], v[40:41], v[136:137]
	v_pk_mul_f32 v[36:37], v[36:37], v[140:141]
	v_pk_mul_f32 v[34:35], v[34:35], v[138:139]
	v_pk_mul_f32 v[30:31], v[30:31], v[232:233]
	v_pk_mul_f32 v[26:27], v[26:27], v[130:131]
	v_pk_mul_f32 v[22:23], v[22:23], v[134:135]
	v_pk_mul_f32 v[32:33], v[32:33], v[234:235]
	v_pk_mul_f32 v[28:29], v[28:29], v[132:133]
	v_pk_mul_f32 v[24:25], v[24:25], v[136:137]
	v_pk_mul_f32 v[20:21], v[20:21], v[140:141]
	v_pk_mul_f32 v[18:19], v[18:19], v[138:139]
